# bundle + hook loads hoisted before first wait + bit-trick bf16 packs replaced by v_cvt_pk_bf16_f32 in weight-copy code
# speedup vs baseline: 1.0203x; 1.0051x over previous
.LBB0_11:
	s_cmpk_gt_i32 s91, 0x15ff
	s_mov_b64 s[2:3], -1
	s_cbranch_scc0 .LBB0_149
	s_add_i32 s2, s91, 0xffffea00
	s_cmpk_gt_u32 s2, 0xaff
	s_mov_b64 s[2:3], -1
	s_cbranch_scc0 .LBB0_146
	s_add_i32 s10, s91, 0xffffdf00
	s_cmpk_gt_u32 s10, 0x141f
	s_cbranch_scc0 .LBB0_27
	s_add_i32 s2, s91, 0xffffcae0
	s_cmpk_gt_u32 s2, 0x1ff
	s_mov_b64 s[2:3], -1
	s_cbranch_scc0 .LBB0_24
	s_add_i32 s2, s91, 0xffffc8e0
	s_cmpk_gt_u32 s2, 0x1ff
	s_mov_b64 s[2:3], -1
	s_cbranch_scc0 .LBB0_21
	s_add_i32 s2, s91, 0xffffc6e0
	s_cmpk_gt_u32 s2, 0xff
	s_mov_b64 s[2:3], -1
	s_cbranch_scc0 .LBB0_18
	s_and_b32 s3, s15, 0x1ffc0
	s_and_b32 s2, s5, 0x7c0
	v_or_b32_e32 v2, s3, v84
	v_or_b32_e32 v1, s2, v85
	v_lshlrev_b32_e32 v66, 13, v2
	s_waitcnt lgkmcnt(0)
	v_lshl_add_u64 v[2:3], s[42:43], 0, v[66:67]
	v_lshlrev_b32_e32 v66, 2, v1
	v_lshl_add_u64 v[62:63], v[2:3], 0, v[66:67]
	v_add_co_u32_e32 v6, vcc, 0x8000, v62
	s_lshl_b32 s8, s3, 1
	s_nop 0
	v_addc_co_u32_e32 v7, vcc, 0, v63, vcc
	v_add_co_u32_e32 v10, vcc, 0x10000, v62
	global_load_dwordx4 v[2:5], v[62:63], off
	s_nop 0
	global_load_dwordx4 v[6:9], v[6:7], off
	v_addc_co_u32_e32 v11, vcc, 0, v63, vcc
	v_add_co_u32_e32 v14, vcc, 0x18000, v62
	v_or_b32_e32 v1, s2, v87
	s_nop 0
	v_addc_co_u32_e32 v15, vcc, 0, v63, vcc
	v_add_co_u32_e32 v18, vcc, 0x20000, v62
	global_load_dwordx4 v[10:13], v[10:11], off
	s_nop 0
	global_load_dwordx4 v[14:17], v[14:15], off
	v_addc_co_u32_e32 v19, vcc, 0, v63, vcc
	v_add_co_u32_e32 v22, vcc, 0x28000, v62
	v_lshlrev_b32_e32 v66, 12, v1
	s_nop 0
	v_addc_co_u32_e32 v23, vcc, 0, v63, vcc
	v_add_co_u32_e32 v26, vcc, 0x30000, v62
	global_load_dwordx4 v[18:21], v[18:19], off
	s_nop 0
	global_load_dwordx4 v[22:25], v[22:23], off
	v_addc_co_u32_e32 v27, vcc, 0, v63, vcc
	v_add_co_u32_e32 v30, vcc, 0x38000, v62
	v_or_b32_e32 v1, s2, v89
	s_nop 0
	v_addc_co_u32_e32 v31, vcc, 0, v63, vcc
	v_add_co_u32_e32 v34, vcc, 0x40000, v62
	global_load_dwordx4 v[26:29], v[26:27], off
	s_nop 0
	global_load_dwordx4 v[30:33], v[30:31], off
	v_addc_co_u32_e32 v35, vcc, 0, v63, vcc
	v_add_co_u32_e32 v38, vcc, 0x48000, v62
	s_nop 1
	v_addc_co_u32_e32 v39, vcc, 0, v63, vcc
	v_add_co_u32_e32 v42, vcc, 0x50000, v62
	global_load_dwordx4 v[34:37], v[34:35], off
	s_nop 0
	global_load_dwordx4 v[38:41], v[38:39], off
	v_addc_co_u32_e32 v43, vcc, 0, v63, vcc
	v_add_co_u32_e32 v46, vcc, 0x58000, v62
	s_nop 1
	v_addc_co_u32_e32 v47, vcc, 0, v63, vcc
	v_add_co_u32_e32 v50, vcc, 0x60000, v62
	global_load_dwordx4 v[42:45], v[42:43], off
	s_nop 0
	global_load_dwordx4 v[46:49], v[46:47], off
	v_addc_co_u32_e32 v51, vcc, 0, v63, vcc
	v_add_co_u32_e32 v54, vcc, 0x68000, v62
	s_nop 1
	v_addc_co_u32_e32 v55, vcc, 0, v63, vcc
	global_load_dwordx4 v[50:53], v[50:51], off
	s_nop 0
	global_load_dwordx4 v[54:57], v[54:55], off
	v_add_co_u32_e32 v58, vcc, 0x70000, v62
	s_nop 1
	v_addc_co_u32_e32 v59, vcc, 0, v63, vcc
	global_load_dwordx4 v[58:61], v[58:59], off
	v_add_co_u32_e32 v62, vcc, 0x78000, v62
	s_nop 1
	v_addc_co_u32_e32 v63, vcc, 0, v63, vcc
	global_load_dwordx4 v[62:65], v[62:63], off
	s_waitcnt vmcnt(15)
	ds_write2_b32 v86, v2, v3 offset1:1
	ds_write2_b32 v86, v4, v5 offset0:2 offset1:3
	s_waitcnt vmcnt(14)
	ds_write2_b32 v96, v6, v7 offset1:1
	ds_write2_b32 v97, v8, v9 offset1:1
	s_waitcnt vmcnt(13)
	ds_write2_b32 v98, v10, v11 offset1:1
	ds_write2_b32 v99, v12, v13 offset1:1
	s_waitcnt vmcnt(12)
	ds_write2_b32 v100, v14, v15 offset1:1
	ds_write2_b32 v101, v16, v17 offset1:1
	s_waitcnt vmcnt(11)
	ds_write2_b32 v102, v18, v19 offset1:1
	ds_write2_b32 v103, v20, v21 offset1:1
	s_waitcnt vmcnt(10)
	ds_write2_b32 v104, v22, v23 offset1:1
	ds_write2_b32 v105, v24, v25 offset1:1
	s_waitcnt vmcnt(9)
	ds_write2_b32 v106, v26, v27 offset1:1
	ds_write2_b32 v107, v28, v29 offset1:1
	s_waitcnt vmcnt(8)
	ds_write2_b32 v108, v30, v31 offset1:1
	ds_write2_b32 v109, v32, v33 offset1:1
	s_waitcnt vmcnt(7)
	ds_write2_b32 v110, v34, v35 offset1:1
	ds_write2_b32 v111, v36, v37 offset1:1
	s_waitcnt vmcnt(6)
	ds_write2_b32 v112, v38, v39 offset1:1
	ds_write2_b32 v113, v40, v41 offset1:1
	s_waitcnt vmcnt(5)
	ds_write2_b32 v114, v42, v43 offset1:1
	ds_write2_b32 v115, v44, v45 offset1:1
	s_waitcnt vmcnt(4)
	ds_write2_b32 v116, v46, v47 offset1:1
	ds_write2_b32 v117, v48, v49 offset1:1
	s_waitcnt vmcnt(3)
	ds_write2_b32 v118, v50, v51 offset1:1
	ds_write2_b32 v119, v52, v53 offset1:1
	s_waitcnt vmcnt(2)
	ds_write2_b32 v120, v54, v55 offset1:1
	ds_write2_b32 v121, v56, v57 offset1:1
	s_waitcnt vmcnt(1)
	ds_write2_b32 v122, v58, v59 offset1:1
	ds_write2_b32 v123, v60, v61 offset1:1
	s_waitcnt vmcnt(0)
	ds_write2_b32 v124, v62, v63 offset1:1
	ds_write2_b32 v125, v64, v65 offset1:1
	s_waitcnt lgkmcnt(0)
	ds_read2_b32 v[10:11], v126 offset0:134 offset1:142
	ds_read2_b32 v[8:9], v126 offset0:199 offset1:207
	ds_read2_b32 v[14:15], v126 offset0:4 offset1:12
	ds_read2_b32 v[12:13], v126 offset0:69 offset1:77
	ds_read2_b32 v[18:19], v88 offset0:130 offset1:138
	s_waitcnt lgkmcnt(4)
	s_waitcnt lgkmcnt(3)
	ds_read2_b32 v[16:17], v88 offset0:195 offset1:203
	v_cvt_pk_bf16_f32 v7, v10, v8
	s_waitcnt lgkmcnt(3)
	ds_read2_b32 v[22:23], v88 offset1:8
	s_waitcnt lgkmcnt(3)
	ds_read2_b32 v[20:21], v88 offset0:65 offset1:73
	v_cvt_pk_bf16_f32 v6, v14, v12
	s_waitcnt lgkmcnt(3)
	s_waitcnt lgkmcnt(2)
	s_waitcnt lgkmcnt(1)
	v_cvt_pk_bf16_f32 v5, v18, v16
	s_waitcnt lgkmcnt(0)
	v_lshl_add_u64 v[2:3], v[68:69], 0, s[8:9]
	v_cvt_pk_bf16_f32 v4, v22, v20
	v_lshl_add_u64 v[24:25], v[2:3], 0, v[66:67]
	global_store_dwordx4 v[24:25], v[4:7], off
	s_nop 1
	v_cvt_pk_bf16_f32 v7, v11, v9
	v_cvt_pk_bf16_f32 v6, v15, v13
	v_cvt_pk_bf16_f32 v5, v19, v17
	ds_read2_b32 v[12:13], v126 offset0:150 offset1:158
	v_cvt_pk_bf16_f32 v4, v23, v21
	ds_read2_b32 v[8:9], v126 offset0:215 offset1:223
	v_lshlrev_b32_e32 v66, 12, v1
	v_lshl_add_u64 v[10:11], v[2:3], 0, v[66:67]
	ds_read2_b32 v[14:15], v126 offset0:20 offset1:28
	global_store_dwordx4 v[10:11], v[4:7], off
	ds_read2_b32 v[10:11], v126 offset0:85 offset1:93
	ds_read2_b32 v[18:19], v88 offset0:146 offset1:154
	s_waitcnt lgkmcnt(4)
	s_waitcnt lgkmcnt(3)
	ds_read2_b32 v[16:17], v88 offset0:211 offset1:219
	v_cvt_pk_bf16_f32 v7, v12, v8
	s_waitcnt lgkmcnt(3)
	ds_read2_b32 v[22:23], v88 offset0:16 offset1:24
	s_waitcnt lgkmcnt(3)
	ds_read2_b32 v[20:21], v88 offset0:81 offset1:89
	v_cvt_pk_bf16_f32 v6, v14, v10
	s_waitcnt lgkmcnt(3)
	s_waitcnt lgkmcnt(2)
	s_waitcnt lgkmcnt(1)
	v_or_b32_e32 v1, s2, v90
	v_cvt_pk_bf16_f32 v5, v18, v16
	s_waitcnt lgkmcnt(0)
	v_lshlrev_b32_e32 v66, 12, v1
	v_cvt_pk_bf16_f32 v4, v22, v20
	v_lshl_add_u64 v[24:25], v[2:3], 0, v[66:67]
	global_store_dwordx4 v[24:25], v[4:7], off
	s_nop 1
	v_cvt_pk_bf16_f32 v7, v13, v9
	v_cvt_pk_bf16_f32 v6, v15, v11
	v_cvt_pk_bf16_f32 v5, v19, v17
	ds_read2_b32 v[12:13], v126 offset0:166 offset1:174
	v_or_b32_e32 v1, s2, v91
	v_cvt_pk_bf16_f32 v4, v23, v21
	ds_read2_b32 v[8:9], v126 offset0:231 offset1:239
	v_lshlrev_b32_e32 v66, 12, v1
	v_lshl_add_u64 v[10:11], v[2:3], 0, v[66:67]
	ds_read2_b32 v[14:15], v126 offset0:36 offset1:44
	global_store_dwordx4 v[10:11], v[4:7], off
	ds_read2_b32 v[10:11], v126 offset0:101 offset1:109
	ds_read2_b32 v[18:19], v88 offset0:162 offset1:170
	s_waitcnt lgkmcnt(4)
	s_waitcnt lgkmcnt(3)
	ds_read2_b32 v[16:17], v88 offset0:227 offset1:235
	v_cvt_pk_bf16_f32 v7, v12, v8
	s_waitcnt lgkmcnt(3)
	ds_read2_b32 v[22:23], v88 offset0:32 offset1:40
	s_waitcnt lgkmcnt(3)
	ds_read2_b32 v[20:21], v88 offset0:97 offset1:105
	v_cvt_pk_bf16_f32 v6, v14, v10
	s_waitcnt lgkmcnt(3)
	s_waitcnt lgkmcnt(2)
	s_waitcnt lgkmcnt(1)
	v_or_b32_e32 v1, s2, v92
	v_cvt_pk_bf16_f32 v5, v18, v16
	s_waitcnt lgkmcnt(0)
	v_lshlrev_b32_e32 v66, 12, v1
	v_cvt_pk_bf16_f32 v4, v22, v20
	v_lshl_add_u64 v[24:25], v[2:3], 0, v[66:67]
	global_store_dwordx4 v[24:25], v[4:7], off
	s_nop 1
	v_cvt_pk_bf16_f32 v7, v13, v9
	v_cvt_pk_bf16_f32 v6, v15, v11
	v_cvt_pk_bf16_f32 v5, v19, v17
	ds_read2_b32 v[12:13], v126 offset0:182 offset1:190
	v_or_b32_e32 v1, s2, v93
	v_cvt_pk_bf16_f32 v4, v23, v21
	ds_read2_b32 v[8:9], v126 offset0:247 offset1:255
	v_lshlrev_b32_e32 v66, 12, v1
	v_lshl_add_u64 v[10:11], v[2:3], 0, v[66:67]
	ds_read2_b32 v[14:15], v126 offset0:52 offset1:60
	global_store_dwordx4 v[10:11], v[4:7], off
	ds_read2_b32 v[10:11], v126 offset0:117 offset1:125
	ds_read2_b32 v[18:19], v88 offset0:178 offset1:186
	s_waitcnt lgkmcnt(4)
	s_waitcnt lgkmcnt(3)
	ds_read2_b32 v[16:17], v88 offset0:243 offset1:251
	v_cvt_pk_bf16_f32 v7, v12, v8
	s_waitcnt lgkmcnt(3)
	ds_read2_b32 v[22:23], v88 offset0:48 offset1:56
	s_waitcnt lgkmcnt(3)
	ds_read2_b32 v[20:21], v88 offset0:113 offset1:121
	v_cvt_pk_bf16_f32 v6, v14, v10
	s_waitcnt lgkmcnt(3)
	s_waitcnt lgkmcnt(2)
	s_waitcnt lgkmcnt(1)
	v_or_b32_e32 v1, s2, v94
	v_cvt_pk_bf16_f32 v5, v18, v16
	s_waitcnt lgkmcnt(0)
	v_lshlrev_b32_e32 v66, 12, v1
	v_cvt_pk_bf16_f32 v4, v22, v20
	v_lshl_add_u64 v[24:25], v[2:3], 0, v[66:67]
	global_store_dwordx4 v[24:25], v[4:7], off
	v_bfe_u32 v8, v23, 16, 1
	v_or_b32_e32 v1, s2, v95
	v_cvt_pk_bf16_f32 v7, v13, v9
	v_cvt_pk_bf16_f32 v6, v15, v11
	v_cvt_pk_bf16_f32 v5, v19, v17
	v_bfe_u32 v4, v21, 16, 1
	v_add3_u32 v8, v23, v8, s29
	v_add3_u32 v4, v21, v4, s29
	v_lshrrev_b32_e32 v8, 16, v8
	v_lshlrev_b32_e32 v66, 12, v1
	v_and_or_b32 v4, v4, s31, v8
	v_lshl_add_u64 v[2:3], v[2:3], 0, v[66:67]
	global_store_dwordx4 v[2:3], v[4:7], off
	s_waitcnt lgkmcnt(0)
	s_mov_b64 s[2:3], 0
.LBB0_18:
	s_andn2_b64 vcc, exec, s[2:3]
	s_cbranch_vccnz .LBB0_20
	s_add_i32 s2, s15, 0xfffe0200
	s_and_b32 s3, s2, 0x1c0
	s_and_b32 s2, s5, 0x7c0
	v_or_b32_e32 v2, s3, v84
	v_or_b32_e32 v1, s2, v85
	v_lshlrev_b32_e32 v66, 13, v2
	s_waitcnt lgkmcnt(0)
	v_lshl_add_u64 v[2:3], s[40:41], 0, v[66:67]
	v_lshlrev_b32_e32 v66, 2, v1
	v_lshl_add_u64 v[62:63], v[2:3], 0, v[66:67]
	v_add_co_u32_e32 v6, vcc, 0x8000, v62
	s_lshl_b32 s8, s3, 1
	s_nop 0
	v_addc_co_u32_e32 v7, vcc, 0, v63, vcc
	v_add_co_u32_e32 v10, vcc, 0x10000, v62
	global_load_dwordx4 v[2:5], v[62:63], off
	s_nop 0
	global_load_dwordx4 v[6:9], v[6:7], off
	v_addc_co_u32_e32 v11, vcc, 0, v63, vcc
	v_add_co_u32_e32 v14, vcc, 0x18000, v62
	v_or_b32_e32 v1, s2, v87
	s_nop 0
	v_addc_co_u32_e32 v15, vcc, 0, v63, vcc
	v_add_co_u32_e32 v18, vcc, 0x20000, v62
	global_load_dwordx4 v[10:13], v[10:11], off
	s_nop 0
	global_load_dwordx4 v[14:17], v[14:15], off
	v_addc_co_u32_e32 v19, vcc, 0, v63, vcc
	v_add_co_u32_e32 v22, vcc, 0x28000, v62
	v_lshlrev_b32_e32 v66, 12, v1
	s_nop 0
	v_addc_co_u32_e32 v23, vcc, 0, v63, vcc
	v_add_co_u32_e32 v26, vcc, 0x30000, v62
	global_load_dwordx4 v[18:21], v[18:19], off
	s_nop 0
	global_load_dwordx4 v[22:25], v[22:23], off
	v_addc_co_u32_e32 v27, vcc, 0, v63, vcc
	v_add_co_u32_e32 v30, vcc, 0x38000, v62
	v_or_b32_e32 v1, s2, v89
	s_nop 0
	v_addc_co_u32_e32 v31, vcc, 0, v63, vcc
	v_add_co_u32_e32 v34, vcc, 0x40000, v62
	global_load_dwordx4 v[26:29], v[26:27], off
	s_nop 0
	global_load_dwordx4 v[30:33], v[30:31], off
	v_addc_co_u32_e32 v35, vcc, 0, v63, vcc
	v_add_co_u32_e32 v38, vcc, 0x48000, v62
	s_nop 1
	v_addc_co_u32_e32 v39, vcc, 0, v63, vcc
	v_add_co_u32_e32 v42, vcc, 0x50000, v62
	global_load_dwordx4 v[34:37], v[34:35], off
	s_nop 0
	global_load_dwordx4 v[38:41], v[38:39], off
	v_addc_co_u32_e32 v43, vcc, 0, v63, vcc
	v_add_co_u32_e32 v46, vcc, 0x58000, v62
	s_nop 1
	v_addc_co_u32_e32 v47, vcc, 0, v63, vcc
	v_add_co_u32_e32 v50, vcc, 0x60000, v62
	global_load_dwordx4 v[42:45], v[42:43], off
	s_nop 0
	global_load_dwordx4 v[46:49], v[46:47], off
	v_addc_co_u32_e32 v51, vcc, 0, v63, vcc
	v_add_co_u32_e32 v54, vcc, 0x68000, v62
	s_nop 1
	v_addc_co_u32_e32 v55, vcc, 0, v63, vcc
	global_load_dwordx4 v[50:53], v[50:51], off
	s_nop 0
	global_load_dwordx4 v[54:57], v[54:55], off
	v_add_co_u32_e32 v58, vcc, 0x70000, v62
	s_nop 1
	v_addc_co_u32_e32 v59, vcc, 0, v63, vcc
	global_load_dwordx4 v[58:61], v[58:59], off
	v_add_co_u32_e32 v62, vcc, 0x78000, v62
	s_nop 1
	v_addc_co_u32_e32 v63, vcc, 0, v63, vcc
	global_load_dwordx4 v[62:65], v[62:63], off
	s_waitcnt vmcnt(15)
	ds_write2_b32 v86, v2, v3 offset1:1
	ds_write2_b32 v86, v4, v5 offset0:2 offset1:3
	s_waitcnt vmcnt(14)
	ds_write2_b32 v96, v6, v7 offset1:1
	ds_write2_b32 v97, v8, v9 offset1:1
	s_waitcnt vmcnt(13)
	ds_write2_b32 v98, v10, v11 offset1:1
	ds_write2_b32 v99, v12, v13 offset1:1
	s_waitcnt vmcnt(12)
	ds_write2_b32 v100, v14, v15 offset1:1
	ds_write2_b32 v101, v16, v17 offset1:1
	s_waitcnt vmcnt(11)
	ds_write2_b32 v102, v18, v19 offset1:1
	ds_write2_b32 v103, v20, v21 offset1:1
	s_waitcnt vmcnt(10)
	ds_write2_b32 v104, v22, v23 offset1:1
	ds_write2_b32 v105, v24, v25 offset1:1
	s_waitcnt vmcnt(9)
	ds_write2_b32 v106, v26, v27 offset1:1
	ds_write2_b32 v107, v28, v29 offset1:1
	s_waitcnt vmcnt(8)
	ds_write2_b32 v108, v30, v31 offset1:1
	ds_write2_b32 v109, v32, v33 offset1:1
	s_waitcnt vmcnt(7)
	ds_write2_b32 v110, v34, v35 offset1:1
	ds_write2_b32 v111, v36, v37 offset1:1
	s_waitcnt vmcnt(6)
	ds_write2_b32 v112, v38, v39 offset1:1
	ds_write2_b32 v113, v40, v41 offset1:1
	s_waitcnt vmcnt(5)
	ds_write2_b32 v114, v42, v43 offset1:1
	ds_write2_b32 v115, v44, v45 offset1:1
	s_waitcnt vmcnt(4)
	ds_write2_b32 v116, v46, v47 offset1:1
	ds_write2_b32 v117, v48, v49 offset1:1
	s_waitcnt vmcnt(3)
	ds_write2_b32 v118, v50, v51 offset1:1
	ds_write2_b32 v119, v52, v53 offset1:1
	s_waitcnt vmcnt(2)
	ds_write2_b32 v120, v54, v55 offset1:1
	ds_write2_b32 v121, v56, v57 offset1:1
	s_waitcnt vmcnt(1)
	ds_write2_b32 v122, v58, v59 offset1:1
	ds_write2_b32 v123, v60, v61 offset1:1
	s_waitcnt vmcnt(0)
	ds_write2_b32 v124, v62, v63 offset1:1
	ds_write2_b32 v125, v64, v65 offset1:1
	s_waitcnt lgkmcnt(0)
	ds_read2_b32 v[10:11], v126 offset0:134 offset1:142
	ds_read2_b32 v[8:9], v126 offset0:199 offset1:207
	ds_read2_b32 v[14:15], v126 offset0:4 offset1:12
	ds_read2_b32 v[12:13], v126 offset0:69 offset1:77
	ds_read2_b32 v[18:19], v88 offset0:130 offset1:138
	s_waitcnt lgkmcnt(4)
	s_waitcnt lgkmcnt(3)
	ds_read2_b32 v[16:17], v88 offset0:195 offset1:203
	v_cvt_pk_bf16_f32 v7, v10, v8
	s_waitcnt lgkmcnt(3)
	ds_read2_b32 v[22:23], v88 offset1:8
	s_waitcnt lgkmcnt(3)
	ds_read2_b32 v[20:21], v88 offset0:65 offset1:73
	v_cvt_pk_bf16_f32 v6, v14, v12
	s_waitcnt lgkmcnt(3)
	s_waitcnt lgkmcnt(2)
	s_waitcnt lgkmcnt(1)
	v_cvt_pk_bf16_f32 v5, v18, v16
	s_waitcnt lgkmcnt(0)
	v_lshl_add_u64 v[2:3], v[70:71], 0, s[8:9]
	v_cvt_pk_bf16_f32 v4, v22, v20
	v_lshl_add_u64 v[24:25], v[2:3], 0, v[66:67]
	global_store_dwordx4 v[24:25], v[4:7], off
	s_nop 1
	v_cvt_pk_bf16_f32 v7, v11, v9
	v_cvt_pk_bf16_f32 v6, v15, v13
	v_cvt_pk_bf16_f32 v5, v19, v17
	ds_read2_b32 v[12:13], v126 offset0:150 offset1:158
	v_cvt_pk_bf16_f32 v4, v23, v21
	ds_read2_b32 v[8:9], v126 offset0:215 offset1:223
	v_lshlrev_b32_e32 v66, 12, v1
	v_lshl_add_u64 v[10:11], v[2:3], 0, v[66:67]
	ds_read2_b32 v[14:15], v126 offset0:20 offset1:28
	global_store_dwordx4 v[10:11], v[4:7], off
	ds_read2_b32 v[10:11], v126 offset0:85 offset1:93
	ds_read2_b32 v[18:19], v88 offset0:146 offset1:154
	s_waitcnt lgkmcnt(4)
	s_waitcnt lgkmcnt(3)
	ds_read2_b32 v[16:17], v88 offset0:211 offset1:219
	v_cvt_pk_bf16_f32 v7, v12, v8
	s_waitcnt lgkmcnt(3)
	ds_read2_b32 v[22:23], v88 offset0:16 offset1:24
	s_waitcnt lgkmcnt(3)
	ds_read2_b32 v[20:21], v88 offset0:81 offset1:89
	v_cvt_pk_bf16_f32 v6, v14, v10
	s_waitcnt lgkmcnt(3)
	s_waitcnt lgkmcnt(2)
	s_waitcnt lgkmcnt(1)
	v_or_b32_e32 v1, s2, v90
	v_cvt_pk_bf16_f32 v5, v18, v16
	s_waitcnt lgkmcnt(0)
	v_lshlrev_b32_e32 v66, 12, v1
	v_cvt_pk_bf16_f32 v4, v22, v20
	v_lshl_add_u64 v[24:25], v[2:3], 0, v[66:67]
	global_store_dwordx4 v[24:25], v[4:7], off
	s_nop 1
	v_cvt_pk_bf16_f32 v7, v13, v9
	v_cvt_pk_bf16_f32 v6, v15, v11
	v_cvt_pk_bf16_f32 v5, v19, v17
	ds_read2_b32 v[12:13], v126 offset0:166 offset1:174
	v_or_b32_e32 v1, s2, v91
	v_cvt_pk_bf16_f32 v4, v23, v21
	ds_read2_b32 v[8:9], v126 offset0:231 offset1:239
	v_lshlrev_b32_e32 v66, 12, v1
	v_lshl_add_u64 v[10:11], v[2:3], 0, v[66:67]
	ds_read2_b32 v[14:15], v126 offset0:36 offset1:44
	global_store_dwordx4 v[10:11], v[4:7], off
	ds_read2_b32 v[10:11], v126 offset0:101 offset1:109
	ds_read2_b32 v[18:19], v88 offset0:162 offset1:170
	s_waitcnt lgkmcnt(4)
	s_waitcnt lgkmcnt(3)
	ds_read2_b32 v[16:17], v88 offset0:227 offset1:235
	v_cvt_pk_bf16_f32 v7, v12, v8
	s_waitcnt lgkmcnt(3)
	ds_read2_b32 v[22:23], v88 offset0:32 offset1:40
	s_waitcnt lgkmcnt(3)
	ds_read2_b32 v[20:21], v88 offset0:97 offset1:105
	v_cvt_pk_bf16_f32 v6, v14, v10
	s_waitcnt lgkmcnt(3)
	s_waitcnt lgkmcnt(2)
	s_waitcnt lgkmcnt(1)
	v_or_b32_e32 v1, s2, v92
	v_cvt_pk_bf16_f32 v5, v18, v16
	s_waitcnt lgkmcnt(0)
	v_lshlrev_b32_e32 v66, 12, v1
	v_cvt_pk_bf16_f32 v4, v22, v20
	v_lshl_add_u64 v[24:25], v[2:3], 0, v[66:67]
	global_store_dwordx4 v[24:25], v[4:7], off
	s_nop 1
	v_cvt_pk_bf16_f32 v7, v13, v9
	v_cvt_pk_bf16_f32 v6, v15, v11
	v_cvt_pk_bf16_f32 v5, v19, v17
	ds_read2_b32 v[12:13], v126 offset0:182 offset1:190
	v_or_b32_e32 v1, s2, v93
	v_cvt_pk_bf16_f32 v4, v23, v21
	ds_read2_b32 v[8:9], v126 offset0:247 offset1:255
	v_lshlrev_b32_e32 v66, 12, v1
	v_lshl_add_u64 v[10:11], v[2:3], 0, v[66:67]
	ds_read2_b32 v[14:15], v126 offset0:52 offset1:60
	global_store_dwordx4 v[10:11], v[4:7], off
	ds_read2_b32 v[10:11], v126 offset0:117 offset1:125
	ds_read2_b32 v[18:19], v88 offset0:178 offset1:186
	s_waitcnt lgkmcnt(4)
	s_waitcnt lgkmcnt(3)
	ds_read2_b32 v[16:17], v88 offset0:243 offset1:251
	v_cvt_pk_bf16_f32 v7, v12, v8
	s_waitcnt lgkmcnt(3)
	ds_read2_b32 v[22:23], v88 offset0:48 offset1:56
	s_waitcnt lgkmcnt(3)
	ds_read2_b32 v[20:21], v88 offset0:113 offset1:121
	v_cvt_pk_bf16_f32 v6, v14, v10
	s_waitcnt lgkmcnt(3)
	s_waitcnt lgkmcnt(2)
	s_waitcnt lgkmcnt(1)
	v_or_b32_e32 v1, s2, v94
	v_cvt_pk_bf16_f32 v5, v18, v16
	s_waitcnt lgkmcnt(0)
	v_lshlrev_b32_e32 v66, 12, v1
	v_cvt_pk_bf16_f32 v4, v22, v20
	v_lshl_add_u64 v[24:25], v[2:3], 0, v[66:67]
	global_store_dwordx4 v[24:25], v[4:7], off
	v_bfe_u32 v8, v23, 16, 1
	v_or_b32_e32 v1, s2, v95
	v_cvt_pk_bf16_f32 v7, v13, v9
	v_cvt_pk_bf16_f32 v6, v15, v11
	v_cvt_pk_bf16_f32 v5, v19, v17
	v_bfe_u32 v4, v21, 16, 1
	v_add3_u32 v8, v23, v8, s29
	v_add3_u32 v4, v21, v4, s29
	v_lshrrev_b32_e32 v8, 16, v8
	v_lshlrev_b32_e32 v66, 12, v1
	v_and_or_b32 v4, v4, s31, v8
	v_lshl_add_u64 v[2:3], v[2:3], 0, v[66:67]
	global_store_dwordx4 v[2:3], v[4:7], off
	s_waitcnt lgkmcnt(0)

.LBB0_21:
	s_andn2_b64 vcc, exec, s[2:3]
	s_cbranch_vccnz .LBB0_23
	s_and_b32 s3, s17, 0x7c0
	s_and_b32 s2, s5, 0x3c0
	v_or_b32_e32 v2, s3, v84
	v_or_b32_e32 v1, s2, v85
	v_lshlrev_b32_e32 v66, 12, v2
	s_waitcnt lgkmcnt(0)
	v_lshl_add_u64 v[2:3], s[66:67], 0, v[66:67]
	v_lshlrev_b32_e32 v66, 2, v1
	v_lshl_add_u64 v[62:63], v[2:3], 0, v[66:67]
	v_add_co_u32_e32 v6, vcc, 0x4000, v62
	s_mov_b32 s8, 0x8000
	s_nop 0
	v_addc_co_u32_e32 v7, vcc, 0, v63, vcc
	v_add_co_u32_e32 v10, vcc, s8, v62
	s_mov_b32 s8, 0x10000
	s_nop 0
	v_addc_co_u32_e32 v11, vcc, 0, v63, vcc
	v_add_co_u32_e32 v14, vcc, 0xc000, v62
	global_load_dwordx4 v[2:5], v[62:63], off
	s_nop 0
	global_load_dwordx4 v[6:9], v[6:7], off
	v_addc_co_u32_e32 v15, vcc, 0, v63, vcc
	v_add_co_u32_e32 v18, vcc, s8, v62
	s_mov_b32 s8, 0x18000
	s_nop 0
	v_addc_co_u32_e32 v19, vcc, 0, v63, vcc
	v_add_co_u32_e32 v22, vcc, 0x14000, v62
	global_load_dwordx4 v[10:13], v[10:11], off
	s_nop 0
	global_load_dwordx4 v[14:17], v[14:15], off
	v_addc_co_u32_e32 v23, vcc, 0, v63, vcc
	v_add_co_u32_e32 v26, vcc, s8, v62
	s_mov_b32 s8, 0x20000
	s_nop 0
	v_addc_co_u32_e32 v27, vcc, 0, v63, vcc
	v_add_co_u32_e32 v30, vcc, 0x1c000, v62
	global_load_dwordx4 v[18:21], v[18:19], off
	s_nop 0
	global_load_dwordx4 v[22:25], v[22:23], off
	v_addc_co_u32_e32 v31, vcc, 0, v63, vcc
	v_add_co_u32_e32 v34, vcc, s8, v62
	global_load_dwordx4 v[26:29], v[26:27], off
	s_nop 0
	global_load_dwordx4 v[30:33], v[30:31], off
	v_addc_co_u32_e32 v35, vcc, 0, v63, vcc
	v_add_co_u32_e32 v38, vcc, 0x24000, v62
	s_lshl_b32 s8, s3, 1
	s_nop 0
	v_addc_co_u32_e32 v39, vcc, 0, v63, vcc
	v_add_co_u32_e32 v42, vcc, s22, v62
	global_load_dwordx4 v[34:37], v[34:35], off
	s_nop 0
	global_load_dwordx4 v[38:41], v[38:39], off
	v_addc_co_u32_e32 v43, vcc, 0, v63, vcc
	v_add_co_u32_e32 v46, vcc, 0x2c000, v62
	v_or_b32_e32 v1, s2, v87
	s_nop 0
	v_addc_co_u32_e32 v47, vcc, 0, v63, vcc
	v_add_co_u32_e32 v50, vcc, s23, v62
	global_load_dwordx4 v[42:45], v[42:43], off
	s_nop 0
	global_load_dwordx4 v[46:49], v[46:47], off
	v_addc_co_u32_e32 v51, vcc, 0, v63, vcc
	v_add_co_u32_e32 v54, vcc, 0x34000, v62
	v_lshlrev_b32_e32 v66, 12, v1
	s_nop 0
	v_addc_co_u32_e32 v55, vcc, 0, v63, vcc
	global_load_dwordx4 v[50:53], v[50:51], off
	s_nop 0
	global_load_dwordx4 v[54:57], v[54:55], off
	v_add_co_u32_e32 v58, vcc, s28, v62
	v_or_b32_e32 v1, s2, v89
	s_nop 0
	v_addc_co_u32_e32 v59, vcc, 0, v63, vcc
	global_load_dwordx4 v[58:61], v[58:59], off
	v_add_co_u32_e32 v62, vcc, 0x3c000, v62
	s_nop 1
	v_addc_co_u32_e32 v63, vcc, 0, v63, vcc
	global_load_dwordx4 v[62:65], v[62:63], off
	s_waitcnt vmcnt(15)
	ds_write2_b32 v86, v2, v3 offset1:1
	ds_write2_b32 v86, v4, v5 offset0:2 offset1:3
	s_waitcnt vmcnt(14)
	ds_write2_b32 v96, v6, v7 offset1:1
	ds_write2_b32 v97, v8, v9 offset1:1
	s_waitcnt vmcnt(13)
	ds_write2_b32 v98, v10, v11 offset1:1
	ds_write2_b32 v99, v12, v13 offset1:1
	s_waitcnt vmcnt(12)
	ds_write2_b32 v100, v14, v15 offset1:1
	ds_write2_b32 v101, v16, v17 offset1:1
	s_waitcnt vmcnt(11)
	ds_write2_b32 v102, v18, v19 offset1:1
	ds_write2_b32 v103, v20, v21 offset1:1
	s_waitcnt vmcnt(10)
	ds_write2_b32 v104, v22, v23 offset1:1
	ds_write2_b32 v105, v24, v25 offset1:1
	s_waitcnt vmcnt(9)
	ds_write2_b32 v106, v26, v27 offset1:1
	ds_write2_b32 v107, v28, v29 offset1:1
	s_waitcnt vmcnt(8)
	ds_write2_b32 v108, v30, v31 offset1:1
	ds_write2_b32 v109, v32, v33 offset1:1
	s_waitcnt vmcnt(7)
	ds_write2_b32 v110, v34, v35 offset1:1
	ds_write2_b32 v111, v36, v37 offset1:1
	s_waitcnt vmcnt(6)
	ds_write2_b32 v112, v38, v39 offset1:1
	ds_write2_b32 v113, v40, v41 offset1:1
	s_waitcnt vmcnt(5)
	ds_write2_b32 v114, v42, v43 offset1:1
	ds_write2_b32 v115, v44, v45 offset1:1
	s_waitcnt vmcnt(4)
	ds_write2_b32 v116, v46, v47 offset1:1
	ds_write2_b32 v117, v48, v49 offset1:1
	s_waitcnt vmcnt(3)
	ds_write2_b32 v118, v50, v51 offset1:1
	ds_write2_b32 v119, v52, v53 offset1:1
	s_waitcnt vmcnt(2)
	ds_write2_b32 v120, v54, v55 offset1:1
	ds_write2_b32 v121, v56, v57 offset1:1
	s_waitcnt vmcnt(1)
	ds_write2_b32 v122, v58, v59 offset1:1
	ds_write2_b32 v123, v60, v61 offset1:1
	s_waitcnt vmcnt(0)
	ds_write2_b32 v124, v62, v63 offset1:1
	ds_write2_b32 v125, v64, v65 offset1:1
	s_waitcnt lgkmcnt(0)
	ds_read2_b32 v[10:11], v126 offset0:134 offset1:142
	ds_read2_b32 v[8:9], v126 offset0:199 offset1:207
	ds_read2_b32 v[14:15], v126 offset0:4 offset1:12
	ds_read2_b32 v[12:13], v126 offset0:69 offset1:77
	ds_read2_b32 v[18:19], v88 offset0:130 offset1:138
	s_waitcnt lgkmcnt(4)
	s_waitcnt lgkmcnt(3)
	ds_read2_b32 v[16:17], v88 offset0:195 offset1:203
	v_cvt_pk_bf16_f32 v7, v10, v8
	s_waitcnt lgkmcnt(3)
	ds_read2_b32 v[22:23], v88 offset1:8
	s_waitcnt lgkmcnt(3)
	ds_read2_b32 v[20:21], v88 offset0:65 offset1:73
	v_cvt_pk_bf16_f32 v6, v14, v12
	s_waitcnt lgkmcnt(3)
	s_waitcnt lgkmcnt(2)
	s_waitcnt lgkmcnt(1)
	v_cvt_pk_bf16_f32 v5, v18, v16
	s_waitcnt lgkmcnt(0)
	v_lshl_add_u64 v[2:3], v[72:73], 0, s[8:9]
	v_cvt_pk_bf16_f32 v4, v22, v20
	v_lshl_add_u64 v[24:25], v[2:3], 0, v[66:67]
	global_store_dwordx4 v[24:25], v[4:7], off
	s_nop 1
	v_cvt_pk_bf16_f32 v7, v11, v9
	v_cvt_pk_bf16_f32 v6, v15, v13
	v_cvt_pk_bf16_f32 v5, v19, v17
	ds_read2_b32 v[12:13], v126 offset0:150 offset1:158
	v_cvt_pk_bf16_f32 v4, v23, v21
	ds_read2_b32 v[8:9], v126 offset0:215 offset1:223
	v_lshlrev_b32_e32 v66, 12, v1
	v_lshl_add_u64 v[10:11], v[2:3], 0, v[66:67]
	ds_read2_b32 v[14:15], v126 offset0:20 offset1:28
	global_store_dwordx4 v[10:11], v[4:7], off
	ds_read2_b32 v[10:11], v126 offset0:85 offset1:93
	ds_read2_b32 v[18:19], v88 offset0:146 offset1:154
	s_waitcnt lgkmcnt(4)
	s_waitcnt lgkmcnt(3)
	ds_read2_b32 v[16:17], v88 offset0:211 offset1:219
	v_cvt_pk_bf16_f32 v7, v12, v8
	s_waitcnt lgkmcnt(3)
	ds_read2_b32 v[22:23], v88 offset0:16 offset1:24
	s_waitcnt lgkmcnt(3)
	ds_read2_b32 v[20:21], v88 offset0:81 offset1:89
	v_cvt_pk_bf16_f32 v6, v14, v10
	s_waitcnt lgkmcnt(3)
	s_waitcnt lgkmcnt(2)
	s_waitcnt lgkmcnt(1)
	v_or_b32_e32 v1, s2, v90
	v_cvt_pk_bf16_f32 v5, v18, v16
	s_waitcnt lgkmcnt(0)
	v_lshlrev_b32_e32 v66, 12, v1
	v_cvt_pk_bf16_f32 v4, v22, v20
	v_lshl_add_u64 v[24:25], v[2:3], 0, v[66:67]
	global_store_dwordx4 v[24:25], v[4:7], off
	s_nop 1
	v_cvt_pk_bf16_f32 v7, v13, v9
	v_cvt_pk_bf16_f32 v6, v15, v11
	v_cvt_pk_bf16_f32 v5, v19, v17
	ds_read2_b32 v[12:13], v126 offset0:166 offset1:174
	v_or_b32_e32 v1, s2, v91
	v_cvt_pk_bf16_f32 v4, v23, v21
	ds_read2_b32 v[8:9], v126 offset0:231 offset1:239
	v_lshlrev_b32_e32 v66, 12, v1
	v_lshl_add_u64 v[10:11], v[2:3], 0, v[66:67]
	ds_read2_b32 v[14:15], v126 offset0:36 offset1:44
	global_store_dwordx4 v[10:11], v[4:7], off
	ds_read2_b32 v[10:11], v126 offset0:101 offset1:109
	ds_read2_b32 v[18:19], v88 offset0:162 offset1:170
	s_waitcnt lgkmcnt(4)
	s_waitcnt lgkmcnt(3)
	ds_read2_b32 v[16:17], v88 offset0:227 offset1:235
	v_cvt_pk_bf16_f32 v7, v12, v8
	s_waitcnt lgkmcnt(3)
	ds_read2_b32 v[22:23], v88 offset0:32 offset1:40
	s_waitcnt lgkmcnt(3)
	ds_read2_b32 v[20:21], v88 offset0:97 offset1:105
	v_cvt_pk_bf16_f32 v6, v14, v10
	s_waitcnt lgkmcnt(3)
	s_waitcnt lgkmcnt(2)
	s_waitcnt lgkmcnt(1)
	v_or_b32_e32 v1, s2, v92
	v_cvt_pk_bf16_f32 v5, v18, v16
	s_waitcnt lgkmcnt(0)
	v_lshlrev_b32_e32 v66, 12, v1
	v_cvt_pk_bf16_f32 v4, v22, v20
	v_lshl_add_u64 v[24:25], v[2:3], 0, v[66:67]
	global_store_dwordx4 v[24:25], v[4:7], off
	s_nop 1
	v_cvt_pk_bf16_f32 v7, v13, v9
	v_cvt_pk_bf16_f32 v6, v15, v11
	v_cvt_pk_bf16_f32 v5, v19, v17
	ds_read2_b32 v[12:13], v126 offset0:182 offset1:190
	v_or_b32_e32 v1, s2, v93
	v_cvt_pk_bf16_f32 v4, v23, v21
	ds_read2_b32 v[8:9], v126 offset0:247 offset1:255
	v_lshlrev_b32_e32 v66, 12, v1
	v_lshl_add_u64 v[10:11], v[2:3], 0, v[66:67]
	ds_read2_b32 v[14:15], v126 offset0:52 offset1:60
	global_store_dwordx4 v[10:11], v[4:7], off
	ds_read2_b32 v[10:11], v126 offset0:117 offset1:125
	ds_read2_b32 v[18:19], v88 offset0:178 offset1:186
	s_waitcnt lgkmcnt(4)
	s_waitcnt lgkmcnt(3)
	ds_read2_b32 v[16:17], v88 offset0:243 offset1:251
	v_cvt_pk_bf16_f32 v7, v12, v8
	s_waitcnt lgkmcnt(3)
	ds_read2_b32 v[22:23], v88 offset0:48 offset1:56
	s_waitcnt lgkmcnt(3)
	ds_read2_b32 v[20:21], v88 offset0:113 offset1:121
	v_cvt_pk_bf16_f32 v6, v14, v10
	s_waitcnt lgkmcnt(3)
	s_waitcnt lgkmcnt(2)
	s_waitcnt lgkmcnt(1)
	v_or_b32_e32 v1, s2, v94
	v_cvt_pk_bf16_f32 v5, v18, v16
	s_waitcnt lgkmcnt(0)
	v_lshlrev_b32_e32 v66, 12, v1
	v_cvt_pk_bf16_f32 v4, v22, v20
	v_lshl_add_u64 v[24:25], v[2:3], 0, v[66:67]
	global_store_dwordx4 v[24:25], v[4:7], off
	v_bfe_u32 v8, v23, 16, 1
	v_or_b32_e32 v1, s2, v95
	v_cvt_pk_bf16_f32 v7, v13, v9
	v_cvt_pk_bf16_f32 v6, v15, v11
	v_cvt_pk_bf16_f32 v5, v19, v17
	v_bfe_u32 v4, v21, 16, 1
	v_add3_u32 v8, v23, v8, s29
	v_add3_u32 v4, v21, v4, s29
	v_lshrrev_b32_e32 v8, 16, v8
	v_lshlrev_b32_e32 v66, 12, v1
	v_and_or_b32 v4, v4, s31, v8
	v_lshl_add_u64 v[2:3], v[2:3], 0, v[66:67]
	global_store_dwordx4 v[2:3], v[4:7], off
	s_waitcnt lgkmcnt(0)

.LBB0_24:
	s_andn2_b64 vcc, exec, s[2:3]
	s_cbranch_vccnz .LBB0_26
	s_add_i32 s2, s15, 0xfffe0a00
	s_and_b32 s3, s2, 0x3c0
	s_and_b32 s2, s5, 0x7c0
	v_or_b32_e32 v2, s3, v84
	v_or_b32_e32 v1, s2, v85
	v_lshlrev_b32_e32 v66, 13, v2
	s_waitcnt lgkmcnt(0)
	v_lshl_add_u64 v[2:3], s[64:65], 0, v[66:67]
	v_lshlrev_b32_e32 v66, 2, v1
	v_lshl_add_u64 v[62:63], v[2:3], 0, v[66:67]
	v_add_co_u32_e32 v6, vcc, 0x8000, v62
	s_lshl_b32 s8, s3, 1
	s_nop 0
	v_addc_co_u32_e32 v7, vcc, 0, v63, vcc
	v_add_co_u32_e32 v10, vcc, 0x10000, v62
	global_load_dwordx4 v[2:5], v[62:63], off
	s_nop 0
	global_load_dwordx4 v[6:9], v[6:7], off
	v_addc_co_u32_e32 v11, vcc, 0, v63, vcc
	v_add_co_u32_e32 v14, vcc, 0x18000, v62
	v_or_b32_e32 v1, s2, v87
	s_nop 0
	v_addc_co_u32_e32 v15, vcc, 0, v63, vcc
	v_add_co_u32_e32 v18, vcc, 0x20000, v62
	global_load_dwordx4 v[10:13], v[10:11], off
	s_nop 0
	global_load_dwordx4 v[14:17], v[14:15], off
	v_addc_co_u32_e32 v19, vcc, 0, v63, vcc
	v_add_co_u32_e32 v22, vcc, 0x28000, v62
	v_lshlrev_b32_e32 v66, 12, v1
	s_nop 0
	v_addc_co_u32_e32 v23, vcc, 0, v63, vcc
	v_add_co_u32_e32 v26, vcc, 0x30000, v62
	global_load_dwordx4 v[18:21], v[18:19], off
	s_nop 0
	global_load_dwordx4 v[22:25], v[22:23], off
	v_addc_co_u32_e32 v27, vcc, 0, v63, vcc
	v_add_co_u32_e32 v30, vcc, 0x38000, v62
	v_or_b32_e32 v1, s2, v89
	s_nop 0
	v_addc_co_u32_e32 v31, vcc, 0, v63, vcc
	v_add_co_u32_e32 v34, vcc, 0x40000, v62
	global_load_dwordx4 v[26:29], v[26:27], off
	s_nop 0
	global_load_dwordx4 v[30:33], v[30:31], off
	v_addc_co_u32_e32 v35, vcc, 0, v63, vcc
	v_add_co_u32_e32 v38, vcc, 0x48000, v62
	s_nop 1
	v_addc_co_u32_e32 v39, vcc, 0, v63, vcc
	v_add_co_u32_e32 v42, vcc, 0x50000, v62
	global_load_dwordx4 v[34:37], v[34:35], off
	s_nop 0
	global_load_dwordx4 v[38:41], v[38:39], off
	v_addc_co_u32_e32 v43, vcc, 0, v63, vcc
	v_add_co_u32_e32 v46, vcc, 0x58000, v62
	s_nop 1
	v_addc_co_u32_e32 v47, vcc, 0, v63, vcc
	v_add_co_u32_e32 v50, vcc, 0x60000, v62
	global_load_dwordx4 v[42:45], v[42:43], off
	s_nop 0
	global_load_dwordx4 v[46:49], v[46:47], off
	v_addc_co_u32_e32 v51, vcc, 0, v63, vcc
	v_add_co_u32_e32 v54, vcc, 0x68000, v62
	s_nop 1
	v_addc_co_u32_e32 v55, vcc, 0, v63, vcc
	global_load_dwordx4 v[50:53], v[50:51], off
	s_nop 0
	global_load_dwordx4 v[54:57], v[54:55], off
	v_add_co_u32_e32 v58, vcc, 0x70000, v62
	s_nop 1
	v_addc_co_u32_e32 v59, vcc, 0, v63, vcc
	global_load_dwordx4 v[58:61], v[58:59], off
	v_add_co_u32_e32 v62, vcc, 0x78000, v62
	s_nop 1
	v_addc_co_u32_e32 v63, vcc, 0, v63, vcc
	global_load_dwordx4 v[62:65], v[62:63], off
	s_waitcnt vmcnt(15)
	ds_write2_b32 v86, v2, v3 offset1:1
	ds_write2_b32 v86, v4, v5 offset0:2 offset1:3
	s_waitcnt vmcnt(14)
	ds_write2_b32 v96, v6, v7 offset1:1
	ds_write2_b32 v97, v8, v9 offset1:1
	s_waitcnt vmcnt(13)
	ds_write2_b32 v98, v10, v11 offset1:1
	ds_write2_b32 v99, v12, v13 offset1:1
	s_waitcnt vmcnt(12)
	ds_write2_b32 v100, v14, v15 offset1:1
	ds_write2_b32 v101, v16, v17 offset1:1
	s_waitcnt vmcnt(11)
	ds_write2_b32 v102, v18, v19 offset1:1
	ds_write2_b32 v103, v20, v21 offset1:1
	s_waitcnt vmcnt(10)
	ds_write2_b32 v104, v22, v23 offset1:1
	ds_write2_b32 v105, v24, v25 offset1:1
	s_waitcnt vmcnt(9)
	ds_write2_b32 v106, v26, v27 offset1:1
	ds_write2_b32 v107, v28, v29 offset1:1
	s_waitcnt vmcnt(8)
	ds_write2_b32 v108, v30, v31 offset1:1
	ds_write2_b32 v109, v32, v33 offset1:1
	s_waitcnt vmcnt(7)
	ds_write2_b32 v110, v34, v35 offset1:1
	ds_write2_b32 v111, v36, v37 offset1:1
	s_waitcnt vmcnt(6)
	ds_write2_b32 v112, v38, v39 offset1:1
	ds_write2_b32 v113, v40, v41 offset1:1
	s_waitcnt vmcnt(5)
	ds_write2_b32 v114, v42, v43 offset1:1
	ds_write2_b32 v115, v44, v45 offset1:1
	s_waitcnt vmcnt(4)
	ds_write2_b32 v116, v46, v47 offset1:1
	ds_write2_b32 v117, v48, v49 offset1:1
	s_waitcnt vmcnt(3)
	ds_write2_b32 v118, v50, v51 offset1:1
	ds_write2_b32 v119, v52, v53 offset1:1
	s_waitcnt vmcnt(2)
	ds_write2_b32 v120, v54, v55 offset1:1
	ds_write2_b32 v121, v56, v57 offset1:1
	s_waitcnt vmcnt(1)
	ds_write2_b32 v122, v58, v59 offset1:1
	ds_write2_b32 v123, v60, v61 offset1:1
	s_waitcnt vmcnt(0)
	ds_write2_b32 v124, v62, v63 offset1:1
	ds_write2_b32 v125, v64, v65 offset1:1
	s_waitcnt lgkmcnt(0)
	ds_read2_b32 v[10:11], v126 offset0:134 offset1:142
	ds_read2_b32 v[8:9], v126 offset0:199 offset1:207
	ds_read2_b32 v[14:15], v126 offset0:4 offset1:12
	ds_read2_b32 v[12:13], v126 offset0:69 offset1:77
	ds_read2_b32 v[18:19], v88 offset0:130 offset1:138
	s_waitcnt lgkmcnt(4)
	s_waitcnt lgkmcnt(3)
	ds_read2_b32 v[16:17], v88 offset0:195 offset1:203
	v_cvt_pk_bf16_f32 v7, v10, v8
	s_waitcnt lgkmcnt(3)
	ds_read2_b32 v[22:23], v88 offset1:8
	s_waitcnt lgkmcnt(3)
	ds_read2_b32 v[20:21], v88 offset0:65 offset1:73
	v_cvt_pk_bf16_f32 v6, v14, v12
	s_waitcnt lgkmcnt(3)
	s_waitcnt lgkmcnt(2)
	s_waitcnt lgkmcnt(1)
	v_cvt_pk_bf16_f32 v5, v18, v16
	s_waitcnt lgkmcnt(0)
	v_lshl_add_u64 v[2:3], v[74:75], 0, s[8:9]
	v_cvt_pk_bf16_f32 v4, v22, v20
	v_lshl_add_u64 v[24:25], v[2:3], 0, v[66:67]
	global_store_dwordx4 v[24:25], v[4:7], off
	s_nop 1
	v_cvt_pk_bf16_f32 v7, v11, v9
	v_cvt_pk_bf16_f32 v6, v15, v13
	v_cvt_pk_bf16_f32 v5, v19, v17
	ds_read2_b32 v[12:13], v126 offset0:150 offset1:158
	v_cvt_pk_bf16_f32 v4, v23, v21
	ds_read2_b32 v[8:9], v126 offset0:215 offset1:223
	v_lshlrev_b32_e32 v66, 12, v1
	v_lshl_add_u64 v[10:11], v[2:3], 0, v[66:67]
	ds_read2_b32 v[14:15], v126 offset0:20 offset1:28
	global_store_dwordx4 v[10:11], v[4:7], off
	ds_read2_b32 v[10:11], v126 offset0:85 offset1:93
	ds_read2_b32 v[18:19], v88 offset0:146 offset1:154
	s_waitcnt lgkmcnt(4)
	s_waitcnt lgkmcnt(3)
	ds_read2_b32 v[16:17], v88 offset0:211 offset1:219
	v_cvt_pk_bf16_f32 v7, v12, v8
	s_waitcnt lgkmcnt(3)
	ds_read2_b32 v[22:23], v88 offset0:16 offset1:24
	s_waitcnt lgkmcnt(3)
	ds_read2_b32 v[20:21], v88 offset0:81 offset1:89
	v_cvt_pk_bf16_f32 v6, v14, v10
	s_waitcnt lgkmcnt(3)
	s_waitcnt lgkmcnt(2)
	s_waitcnt lgkmcnt(1)
	v_or_b32_e32 v1, s2, v90
	v_cvt_pk_bf16_f32 v5, v18, v16
	s_waitcnt lgkmcnt(0)
	v_lshlrev_b32_e32 v66, 12, v1
	v_cvt_pk_bf16_f32 v4, v22, v20
	v_lshl_add_u64 v[24:25], v[2:3], 0, v[66:67]
	global_store_dwordx4 v[24:25], v[4:7], off
	s_nop 1
	v_cvt_pk_bf16_f32 v7, v13, v9
	v_cvt_pk_bf16_f32 v6, v15, v11
	v_cvt_pk_bf16_f32 v5, v19, v17
	ds_read2_b32 v[12:13], v126 offset0:166 offset1:174
	v_or_b32_e32 v1, s2, v91
	v_cvt_pk_bf16_f32 v4, v23, v21
	ds_read2_b32 v[8:9], v126 offset0:231 offset1:239
	v_lshlrev_b32_e32 v66, 12, v1
	v_lshl_add_u64 v[10:11], v[2:3], 0, v[66:67]
	ds_read2_b32 v[14:15], v126 offset0:36 offset1:44
	global_store_dwordx4 v[10:11], v[4:7], off
	ds_read2_b32 v[10:11], v126 offset0:101 offset1:109
	ds_read2_b32 v[18:19], v88 offset0:162 offset1:170
	s_waitcnt lgkmcnt(4)
	s_waitcnt lgkmcnt(3)
	ds_read2_b32 v[16:17], v88 offset0:227 offset1:235
	v_cvt_pk_bf16_f32 v7, v12, v8
	s_waitcnt lgkmcnt(3)
	ds_read2_b32 v[22:23], v88 offset0:32 offset1:40
	s_waitcnt lgkmcnt(3)
	ds_read2_b32 v[20:21], v88 offset0:97 offset1:105
	v_cvt_pk_bf16_f32 v6, v14, v10
	s_waitcnt lgkmcnt(3)
	s_waitcnt lgkmcnt(2)
	s_waitcnt lgkmcnt(1)
	v_or_b32_e32 v1, s2, v92
	v_cvt_pk_bf16_f32 v5, v18, v16
	s_waitcnt lgkmcnt(0)
	v_lshlrev_b32_e32 v66, 12, v1
	v_cvt_pk_bf16_f32 v4, v22, v20
	v_lshl_add_u64 v[24:25], v[2:3], 0, v[66:67]
	global_store_dwordx4 v[24:25], v[4:7], off
	s_nop 1
	v_cvt_pk_bf16_f32 v7, v13, v9
	v_cvt_pk_bf16_f32 v6, v15, v11
	v_cvt_pk_bf16_f32 v5, v19, v17
	ds_read2_b32 v[12:13], v126 offset0:182 offset1:190
	v_or_b32_e32 v1, s2, v93
	v_cvt_pk_bf16_f32 v4, v23, v21
	ds_read2_b32 v[8:9], v126 offset0:247 offset1:255
	v_lshlrev_b32_e32 v66, 12, v1
	v_lshl_add_u64 v[10:11], v[2:3], 0, v[66:67]
	ds_read2_b32 v[14:15], v126 offset0:52 offset1:60
	global_store_dwordx4 v[10:11], v[4:7], off
	ds_read2_b32 v[10:11], v126 offset0:117 offset1:125
	ds_read2_b32 v[18:19], v88 offset0:178 offset1:186
	s_waitcnt lgkmcnt(4)
	s_waitcnt lgkmcnt(3)
	ds_read2_b32 v[16:17], v88 offset0:243 offset1:251
	v_cvt_pk_bf16_f32 v7, v12, v8
	s_waitcnt lgkmcnt(3)
	ds_read2_b32 v[22:23], v88 offset0:48 offset1:56
	s_waitcnt lgkmcnt(3)
	ds_read2_b32 v[20:21], v88 offset0:113 offset1:121
	v_cvt_pk_bf16_f32 v6, v14, v10
	s_waitcnt lgkmcnt(3)
	s_waitcnt lgkmcnt(2)
	s_waitcnt lgkmcnt(1)
	v_or_b32_e32 v1, s2, v94
	v_cvt_pk_bf16_f32 v5, v18, v16
	s_waitcnt lgkmcnt(0)
	v_lshlrev_b32_e32 v66, 12, v1
	v_cvt_pk_bf16_f32 v4, v22, v20
	v_lshl_add_u64 v[24:25], v[2:3], 0, v[66:67]
	global_store_dwordx4 v[24:25], v[4:7], off
	v_bfe_u32 v8, v23, 16, 1
	v_or_b32_e32 v1, s2, v95
	v_cvt_pk_bf16_f32 v7, v13, v9
	v_cvt_pk_bf16_f32 v6, v15, v11
	v_cvt_pk_bf16_f32 v5, v19, v17
	v_bfe_u32 v4, v21, 16, 1
	v_add3_u32 v8, v23, v8, s29
	v_add3_u32 v4, v21, v4, s29
	v_lshrrev_b32_e32 v8, 16, v8
	v_lshlrev_b32_e32 v66, 12, v1
	v_and_or_b32 v4, v4, s31, v8
	v_lshl_add_u64 v[2:3], v[2:3], 0, v[66:67]
	global_store_dwordx4 v[2:3], v[4:7], off
	s_waitcnt lgkmcnt(0)

.LBB0_146:
	s_andn2_b64 vcc, exec, s[2:3]
	s_cbranch_vccnz .LBB0_148
	s_add_i32 s2, s15, 0xfffe4840
	s_and_b32 s3, s2, 0x1fc0
	s_and_b32 s2, s5, 0x7c0
	v_or_b32_e32 v2, s3, v84
	v_or_b32_e32 v1, s2, v85
	v_lshlrev_b32_e32 v66, 13, v2
	v_lshl_add_u64 v[2:3], s[76:77], 0, v[66:67]
	v_lshlrev_b32_e32 v66, 2, v1
	v_lshl_add_u64 v[62:63], v[2:3], 0, v[66:67]
	v_add_co_u32_e32 v6, vcc, 0x8000, v62
	v_or_b32_e32 v1, s2, v87
	s_nop 0
	v_addc_co_u32_e32 v7, vcc, 0, v63, vcc
	v_add_co_u32_e32 v10, vcc, 0x10000, v62
	global_load_dwordx4 v[2:5], v[62:63], off
	s_nop 0
	global_load_dwordx4 v[6:9], v[6:7], off
	v_addc_co_u32_e32 v11, vcc, 0, v63, vcc
	v_add_co_u32_e32 v14, vcc, 0x18000, v62
	s_lshl_b32 s8, s3, 1
	s_nop 0
	v_addc_co_u32_e32 v15, vcc, 0, v63, vcc
	v_add_co_u32_e32 v18, vcc, 0x20000, v62
	global_load_dwordx4 v[10:13], v[10:11], off
	s_nop 0
	global_load_dwordx4 v[14:17], v[14:15], off
	v_addc_co_u32_e32 v19, vcc, 0, v63, vcc
	v_add_co_u32_e32 v22, vcc, 0x28000, v62
	v_mul_u32_u24_e32 v1, 0x1600, v1
	s_nop 0
	v_addc_co_u32_e32 v23, vcc, 0, v63, vcc
	v_add_co_u32_e32 v26, vcc, 0x30000, v62
	global_load_dwordx4 v[18:21], v[18:19], off
	s_nop 0
	global_load_dwordx4 v[22:25], v[22:23], off
	v_addc_co_u32_e32 v27, vcc, 0, v63, vcc
	v_add_co_u32_e32 v30, vcc, 0x38000, v62
	v_lshlrev_b32_e32 v66, 1, v1
	s_nop 0
	v_addc_co_u32_e32 v31, vcc, 0, v63, vcc
	v_add_co_u32_e32 v34, vcc, 0x40000, v62
	global_load_dwordx4 v[26:29], v[26:27], off
	s_nop 0
	global_load_dwordx4 v[30:33], v[30:31], off
	v_addc_co_u32_e32 v35, vcc, 0, v63, vcc
	v_add_co_u32_e32 v38, vcc, 0x48000, v62
	v_or_b32_e32 v1, s2, v89
	s_nop 0
	v_addc_co_u32_e32 v39, vcc, 0, v63, vcc
	v_add_co_u32_e32 v42, vcc, 0x50000, v62
	global_load_dwordx4 v[34:37], v[34:35], off
	s_nop 0
	global_load_dwordx4 v[38:41], v[38:39], off
	v_addc_co_u32_e32 v43, vcc, 0, v63, vcc
	v_add_co_u32_e32 v46, vcc, 0x58000, v62
	v_mul_u32_u24_e32 v1, 0x1600, v1
	s_nop 0
	v_addc_co_u32_e32 v47, vcc, 0, v63, vcc
	v_add_co_u32_e32 v50, vcc, 0x60000, v62
	global_load_dwordx4 v[42:45], v[42:43], off
	s_nop 0
	global_load_dwordx4 v[46:49], v[46:47], off
	v_addc_co_u32_e32 v51, vcc, 0, v63, vcc
	v_add_co_u32_e32 v54, vcc, 0x68000, v62
	s_nop 1
	v_addc_co_u32_e32 v55, vcc, 0, v63, vcc
	global_load_dwordx4 v[50:53], v[50:51], off
	s_nop 0
	global_load_dwordx4 v[54:57], v[54:55], off
	v_add_co_u32_e32 v58, vcc, 0x70000, v62
	s_nop 1
	v_addc_co_u32_e32 v59, vcc, 0, v63, vcc
	global_load_dwordx4 v[58:61], v[58:59], off
	v_add_co_u32_e32 v62, vcc, 0x78000, v62
	s_nop 1
	v_addc_co_u32_e32 v63, vcc, 0, v63, vcc
	global_load_dwordx4 v[62:65], v[62:63], off
	s_waitcnt vmcnt(15)
	ds_write2_b32 v86, v2, v3 offset1:1
	ds_write2_b32 v86, v4, v5 offset0:2 offset1:3
	s_waitcnt vmcnt(14)
	ds_write2_b32 v96, v6, v7 offset1:1
	ds_write2_b32 v97, v8, v9 offset1:1
	s_waitcnt vmcnt(13)
	ds_write2_b32 v98, v10, v11 offset1:1
	ds_write2_b32 v99, v12, v13 offset1:1
	s_waitcnt vmcnt(12)
	ds_write2_b32 v100, v14, v15 offset1:1
	ds_write2_b32 v101, v16, v17 offset1:1
	s_waitcnt vmcnt(11)
	ds_write2_b32 v102, v18, v19 offset1:1
	ds_write2_b32 v103, v20, v21 offset1:1
	s_waitcnt vmcnt(10)
	ds_write2_b32 v104, v22, v23 offset1:1
	ds_write2_b32 v105, v24, v25 offset1:1
	s_waitcnt vmcnt(9)
	ds_write2_b32 v106, v26, v27 offset1:1
	ds_write2_b32 v107, v28, v29 offset1:1
	s_waitcnt vmcnt(8)
	ds_write2_b32 v108, v30, v31 offset1:1
	ds_write2_b32 v109, v32, v33 offset1:1
	s_waitcnt vmcnt(7)
	ds_write2_b32 v110, v34, v35 offset1:1
	ds_write2_b32 v111, v36, v37 offset1:1
	s_waitcnt vmcnt(6)
	ds_write2_b32 v112, v38, v39 offset1:1
	ds_write2_b32 v113, v40, v41 offset1:1
	s_waitcnt vmcnt(5)
	ds_write2_b32 v114, v42, v43 offset1:1
	ds_write2_b32 v115, v44, v45 offset1:1
	s_waitcnt vmcnt(4)
	ds_write2_b32 v116, v46, v47 offset1:1
	ds_write2_b32 v117, v48, v49 offset1:1
	s_waitcnt vmcnt(3)
	ds_write2_b32 v118, v50, v51 offset1:1
	ds_write2_b32 v119, v52, v53 offset1:1
	s_waitcnt vmcnt(2)
	ds_write2_b32 v120, v54, v55 offset1:1
	ds_write2_b32 v121, v56, v57 offset1:1
	s_waitcnt vmcnt(1)
	ds_write2_b32 v122, v58, v59 offset1:1
	ds_write2_b32 v123, v60, v61 offset1:1
	s_waitcnt vmcnt(0)
	ds_write2_b32 v124, v62, v63 offset1:1
	ds_write2_b32 v125, v64, v65 offset1:1
	s_waitcnt lgkmcnt(0)
	ds_read2_b32 v[10:11], v126 offset0:134 offset1:142
	ds_read2_b32 v[8:9], v126 offset0:199 offset1:207
	ds_read2_b32 v[14:15], v126 offset0:4 offset1:12
	ds_read2_b32 v[12:13], v126 offset0:69 offset1:77
	ds_read2_b32 v[18:19], v88 offset0:130 offset1:138
	s_waitcnt lgkmcnt(0)
	ds_read2_b32 v[16:17], v88 offset0:195 offset1:203
	v_cvt_pk_bf16_f32 v7, v10, v8
	ds_read2_b32 v[22:23], v88 offset1:8
	ds_read2_b32 v[20:21], v88 offset0:65 offset1:73
	v_cvt_pk_bf16_f32 v6, v14, v12
	s_waitcnt lgkmcnt(2)
	s_waitcnt lgkmcnt(1)
	v_cvt_pk_bf16_f32 v5, v18, v16
	s_waitcnt lgkmcnt(0)
	v_lshl_add_u64 v[2:3], v[78:79], 0, s[8:9]
	v_cvt_pk_bf16_f32 v4, v22, v20
	v_lshl_add_u64 v[24:25], v[2:3], 0, v[66:67]
	global_store_dwordx4 v[24:25], v[4:7], off
	s_nop 1
	v_cvt_pk_bf16_f32 v7, v11, v9
	v_cvt_pk_bf16_f32 v6, v15, v13
	v_cvt_pk_bf16_f32 v5, v19, v17
	ds_read2_b32 v[12:13], v126 offset0:150 offset1:158
	v_cvt_pk_bf16_f32 v4, v23, v21
	ds_read2_b32 v[8:9], v126 offset0:215 offset1:223
	v_lshlrev_b32_e32 v66, 1, v1
	v_lshl_add_u64 v[10:11], v[2:3], 0, v[66:67]
	ds_read2_b32 v[14:15], v126 offset0:20 offset1:28
	global_store_dwordx4 v[10:11], v[4:7], off
	ds_read2_b32 v[10:11], v126 offset0:85 offset1:93
	ds_read2_b32 v[18:19], v88 offset0:146 offset1:154
	s_waitcnt lgkmcnt(4)
	s_waitcnt lgkmcnt(3)
	ds_read2_b32 v[16:17], v88 offset0:211 offset1:219
	v_cvt_pk_bf16_f32 v7, v12, v8
	s_waitcnt lgkmcnt(3)
	ds_read2_b32 v[22:23], v88 offset0:16 offset1:24
	s_waitcnt lgkmcnt(3)
	ds_read2_b32 v[20:21], v88 offset0:81 offset1:89
	v_cvt_pk_bf16_f32 v6, v14, v10
	s_waitcnt lgkmcnt(3)
	s_waitcnt lgkmcnt(2)
	v_or_b32_e32 v1, s2, v90
	s_waitcnt lgkmcnt(1)
	v_cvt_pk_bf16_f32 v5, v18, v16
	s_waitcnt lgkmcnt(0)
	v_mul_u32_u24_e32 v1, 0x1600, v1
	v_lshlrev_b32_e32 v66, 1, v1
	v_cvt_pk_bf16_f32 v4, v22, v20
	v_lshl_add_u64 v[24:25], v[2:3], 0, v[66:67]
	global_store_dwordx4 v[24:25], v[4:7], off
	s_nop 1
	v_cvt_pk_bf16_f32 v7, v13, v9
	v_cvt_pk_bf16_f32 v6, v15, v11
	v_cvt_pk_bf16_f32 v5, v19, v17
	v_or_b32_e32 v1, s2, v91
	ds_read2_b32 v[12:13], v126 offset0:166 offset1:174
	v_cvt_pk_bf16_f32 v4, v23, v21
	v_mul_u32_u24_e32 v1, 0x1600, v1
	ds_read2_b32 v[8:9], v126 offset0:231 offset1:239
	v_lshlrev_b32_e32 v66, 1, v1
	v_lshl_add_u64 v[10:11], v[2:3], 0, v[66:67]
	ds_read2_b32 v[14:15], v126 offset0:36 offset1:44
	global_store_dwordx4 v[10:11], v[4:7], off
	ds_read2_b32 v[10:11], v126 offset0:101 offset1:109
	ds_read2_b32 v[18:19], v88 offset0:162 offset1:170
	s_waitcnt lgkmcnt(4)
	s_waitcnt lgkmcnt(3)
	ds_read2_b32 v[16:17], v88 offset0:227 offset1:235
	v_cvt_pk_bf16_f32 v7, v12, v8
	s_waitcnt lgkmcnt(3)
	ds_read2_b32 v[22:23], v88 offset0:32 offset1:40
	s_waitcnt lgkmcnt(3)
	ds_read2_b32 v[20:21], v88 offset0:97 offset1:105
	v_cvt_pk_bf16_f32 v6, v14, v10
	s_waitcnt lgkmcnt(3)
	s_waitcnt lgkmcnt(2)
	v_or_b32_e32 v1, s2, v92
	s_waitcnt lgkmcnt(1)
	v_cvt_pk_bf16_f32 v5, v18, v16
	s_waitcnt lgkmcnt(0)
	v_mul_u32_u24_e32 v1, 0x1600, v1
	v_lshlrev_b32_e32 v66, 1, v1
	v_cvt_pk_bf16_f32 v4, v22, v20
	v_lshl_add_u64 v[24:25], v[2:3], 0, v[66:67]
	global_store_dwordx4 v[24:25], v[4:7], off
	s_nop 1
	v_cvt_pk_bf16_f32 v7, v13, v9
	v_cvt_pk_bf16_f32 v6, v15, v11
	v_cvt_pk_bf16_f32 v5, v19, v17
	v_or_b32_e32 v1, s2, v93
	ds_read2_b32 v[12:13], v126 offset0:182 offset1:190
	v_cvt_pk_bf16_f32 v4, v23, v21
	v_mul_u32_u24_e32 v1, 0x1600, v1
	ds_read2_b32 v[8:9], v126 offset0:247 offset1:255
	v_lshlrev_b32_e32 v66, 1, v1
	v_lshl_add_u64 v[10:11], v[2:3], 0, v[66:67]
	ds_read2_b32 v[14:15], v126 offset0:52 offset1:60
	global_store_dwordx4 v[10:11], v[4:7], off
	ds_read2_b32 v[10:11], v126 offset0:117 offset1:125
	ds_read2_b32 v[18:19], v88 offset0:178 offset1:186
	s_waitcnt lgkmcnt(4)
	s_waitcnt lgkmcnt(3)
	ds_read2_b32 v[16:17], v88 offset0:243 offset1:251
	v_cvt_pk_bf16_f32 v7, v12, v8
	s_waitcnt lgkmcnt(3)
	ds_read2_b32 v[22:23], v88 offset0:48 offset1:56
	s_waitcnt lgkmcnt(3)
	ds_read2_b32 v[20:21], v88 offset0:113 offset1:121
	v_cvt_pk_bf16_f32 v6, v14, v10
	s_waitcnt lgkmcnt(3)
	s_waitcnt lgkmcnt(2)
	v_or_b32_e32 v1, s2, v94
	s_waitcnt lgkmcnt(1)
	v_cvt_pk_bf16_f32 v5, v18, v16
	s_waitcnt lgkmcnt(0)
	v_mul_u32_u24_e32 v1, 0x1600, v1
	v_lshlrev_b32_e32 v66, 1, v1
	v_cvt_pk_bf16_f32 v4, v22, v20
	v_lshl_add_u64 v[24:25], v[2:3], 0, v[66:67]
	global_store_dwordx4 v[24:25], v[4:7], off
	v_or_b32_e32 v1, s2, v95
	v_bfe_u32 v8, v23, 16, 1
	v_cvt_pk_bf16_f32 v7, v13, v9
	v_cvt_pk_bf16_f32 v6, v15, v11
	v_cvt_pk_bf16_f32 v5, v19, v17
	v_bfe_u32 v4, v21, 16, 1
	v_add3_u32 v8, v23, v8, s29
	v_mul_u32_u24_e32 v1, 0x1600, v1
	v_add3_u32 v4, v21, v4, s29
	v_lshrrev_b32_e32 v8, 16, v8
	v_lshlrev_b32_e32 v66, 1, v1
	v_and_or_b32 v4, v4, s31, v8
	v_lshl_add_u64 v[2:3], v[2:3], 0, v[66:67]
	global_store_dwordx4 v[2:3], v[4:7], off
	s_waitcnt lgkmcnt(0)

.LBB0_382:
	s_lshl_b32 s56, s79, 8
	s_add_i32 s56, s56, s70
	v_or_b32_e32 v198, s56, v179
	v_lshl_or_b32 v196, s80, 8, v207
	v_ashrrev_i32_e32 v199, 31, v198
	v_ashrrev_i32_e32 v197, 31, v196
	v_lshlrev_b64 v[130:131], 11, v[198:199]
	v_lshl_add_u64 v[228:229], v[130:131], 0, v[196:197]
	v_lshl_add_u64 v[130:131], v[228:229], 2, s[68:69]
	global_load_dwordx4 v[212:215], v[130:131], off offset:16
	global_load_dwordx4 v[216:219], v[130:131], off
	global_load_dwordx4 v[220:223], v[130:131], off offset:528
	global_load_dwordx4 v[224:227], v[130:131], off offset:512
	v_or_b32_e32 v130, 16, v198
	v_ashrrev_i32_e32 v131, 31, v130
	v_lshlrev_b64 v[130:131], 11, v[130:131]
	v_lshl_add_u64 v[204:205], v[130:131], 0, v[196:197]
	v_lshl_add_u64 v[130:131], v[204:205], 2, s[68:69]
	global_load_dwordx4 v[170:173], v[130:131], off offset:16
	global_load_dwordx4 v[174:177], v[130:131], off
	global_load_dwordx4 v[162:165], v[130:131], off offset:528
	global_load_dwordx4 v[166:169], v[130:131], off offset:512
	v_or_b32_e32 v130, 32, v198
	v_ashrrev_i32_e32 v131, 31, v130
	v_lshlrev_b64 v[130:131], 11, v[130:131]
	v_lshl_add_u64 v[202:203], v[130:131], 0, v[196:197]
	v_lshl_add_u64 v[130:131], v[202:203], 2, s[68:69]
	global_load_dwordx4 v[154:157], v[130:131], off offset:16
	global_load_dwordx4 v[158:161], v[130:131], off
	global_load_dwordx4 v[146:149], v[130:131], off offset:528
	global_load_dwordx4 v[150:153], v[130:131], off offset:512
	v_or_b32_e32 v130, 48, v198
	v_ashrrev_i32_e32 v131, 31, v130
	v_lshlrev_b64 v[130:131], 11, v[130:131]
	v_lshl_add_u64 v[200:201], v[130:131], 0, v[196:197]
	v_lshl_add_u64 v[134:135], v[200:201], 2, s[68:69]
	global_load_dwordx4 v[138:141], v[134:135], off offset:16
	global_load_dwordx4 v[142:145], v[134:135], off
	global_load_dwordx4 v[130:133], v[134:135], off offset:528
	s_nop 0
	global_load_dwordx4 v[134:137], v[134:135], off offset:512
	v_lshlrev_b64 v[228:229], 1, v[228:229]
	v_cndmask_b32_e64 v1, 0, 1, s[40:41]
	v_lshl_add_u64 v[230:231], s[14:15], 0, v[228:229]
	v_or_b32_e32 v228, 0x100, v228
	v_cmp_ne_u32_e64 s[12:13], 1, v1
	v_lshl_add_u64 v[228:229], s[14:15], 0, v[228:229]
	s_andn2_b64 vcc, exec, s[40:41]
	s_waitcnt vmcnt(0)
	v_pk_fma_f32 v[124:125], v[124:125], 0.5, v[214:215] op_sel_hi:[1,0,1]
	v_pk_fma_f32 v[128:129], v[128:129], 0.5, v[218:219] op_sel_hi:[1,0,1]
	v_pk_fma_f32 v[126:127], v[126:127], 0.5, v[216:217] op_sel_hi:[1,0,1]
	v_pk_fma_f32 v[122:123], v[122:123], 0.5, v[212:213] op_sel_hi:[1,0,1]
	v_pk_fma_f32 v[120:121], v[120:121], 0.5, v[226:227] op_sel_hi:[1,0,1]
	v_pk_fma_f32 v[118:119], v[118:119], 0.5, v[224:225] op_sel_hi:[1,0,1]
	v_pk_fma_f32 v[116:117], v[116:117], 0.5, v[222:223] op_sel_hi:[1,0,1]
	v_pk_fma_f32 v[114:115], v[114:115], 0.5, v[220:221] op_sel_hi:[1,0,1]
	v_cvt_pk_bf16_f32 v212, v126, v127
	v_cvt_pk_bf16_f32 v213, v128, v129
	v_cvt_pk_bf16_f32 v214, v122, v123
	v_cvt_pk_bf16_f32 v215, v124, v125
	global_store_dwordx4 v[230:231], v[212:215], off
	s_nop 0
	s_nop 1
	v_cvt_pk_bf16_f32 v212, v118, v119
	v_cvt_pk_bf16_f32 v213, v120, v121
	v_cvt_pk_bf16_f32 v214, v114, v115
	v_cvt_pk_bf16_f32 v215, v116, v117
	global_store_dwordx4 v[228:229], v[212:215], off
	s_cbranch_vccnz .LBB0_384
	s_nop 0
	v_mov_b32_e32 v212, v126
	v_mov_b32_e32 v126, v129
	v_mov_b32_e32 v129, v120
	v_mov_b32_e32 v213, v118
	v_mov_b32_e32 v118, v127
	v_mov_b32_e32 v127, v121
	v_pk_mul_f32 v[120:121], v[128:129], v[128:129]
	v_mov_b32_e32 v128, v125
	v_mov_b32_e32 v125, v116
	v_mov_b32_e32 v129, v117
	v_pk_mul_f32 v[116:117], v[124:125], v[124:125]
	v_mov_b32_e32 v124, v123
	v_mov_b32_e32 v123, v114
	v_pk_mul_f32 v[118:119], v[118:119], v[118:119]
	v_mov_b32_e32 v125, v115
	v_pk_mul_f32 v[114:115], v[122:123], v[122:123]
	v_pk_fma_f32 v[118:119], v[212:213], v[212:213], v[118:119]
	v_pk_fma_f32 v[120:121], v[126:127], v[126:127], v[120:121]
	v_pk_fma_f32 v[114:115], v[124:125], v[124:125], v[114:115]
	v_pk_fma_f32 v[116:117], v[128:129], v[128:129], v[116:117]
	v_pk_add_f32 v[118:119], v[118:119], v[120:121]
	v_pk_add_f32 v[114:115], v[116:117], v[114:115]
	s_nop 0
	v_pk_add_f32 v[114:115], v[118:119], v[114:115]
	s_nop 0
	v_add_f32_e32 v1, v114, v115
	v_and_b32_e32 v115, 64, v211
	v_xor_b32_e32 v114, 16, v211
	v_add_u32_e32 v115, 64, v115
	v_cmp_lt_i32_e32 vcc, v114, v115
	s_nop 1
	v_cndmask_b32_e32 v114, v211, v114, vcc
	v_lshlrev_b32_e32 v114, 2, v114
	ds_bpermute_b32 v114, v114, v1
	s_waitcnt lgkmcnt(0)
	v_add_f32_e32 v1, v1, v114
	v_xor_b32_e32 v114, 32, v211
	v_cmp_lt_i32_e32 vcc, v114, v115
	s_nop 1
	v_cndmask_b32_e32 v114, v211, v114, vcc
	v_lshlrev_b32_e32 v114, 2, v114
	ds_bpermute_b32 v114, v114, v1
	s_waitcnt lgkmcnt(0)
	v_add_f32_e32 v1, v1, v114
	v_cndmask_b32_e64 v116, 0, v1, s[2:3]
	s_branch .LBB0_385

.LBB0_385:
	v_lshlrev_b64 v[114:115], 1, v[204:205]
	v_lshl_add_u64 v[122:123], s[14:15], 0, v[114:115]
	v_or_b32_e32 v114, 0x100, v114
	v_pk_fma_f32 v[112:113], v[112:113], 0.5, v[176:177] op_sel_hi:[1,0,1]
	v_pk_fma_f32 v[110:111], v[110:111], 0.5, v[174:175] op_sel_hi:[1,0,1]
	v_pk_fma_f32 v[108:109], v[108:109], 0.5, v[172:173] op_sel_hi:[1,0,1]
	v_pk_fma_f32 v[106:107], v[106:107], 0.5, v[170:171] op_sel_hi:[1,0,1]
	v_cvt_pk_bf16_f32 v118, v110, v111
	v_cvt_pk_bf16_f32 v119, v112, v113
	v_pk_fma_f32 v[104:105], v[104:105], 0.5, v[168:169] op_sel_hi:[1,0,1]
	v_cvt_pk_bf16_f32 v120, v106, v107
	v_cvt_pk_bf16_f32 v121, v108, v109
	v_pk_fma_f32 v[102:103], v[102:103], 0.5, v[166:167] op_sel_hi:[1,0,1]
	v_pk_fma_f32 v[100:101], v[100:101], 0.5, v[164:165] op_sel_hi:[1,0,1]
	v_pk_fma_f32 v[98:99], v[98:99], 0.5, v[162:163] op_sel_hi:[1,0,1]
	v_lshl_add_u64 v[114:115], s[14:15], 0, v[114:115]
	s_and_b64 vcc, exec, s[12:13]
	global_store_dwordx4 v[122:123], v[118:121], off
	s_nop 0
	s_nop 1
	v_cvt_pk_bf16_f32 v118, v102, v103
	v_cvt_pk_bf16_f32 v119, v104, v105
	v_cvt_pk_bf16_f32 v120, v98, v99
	v_cvt_pk_bf16_f32 v121, v100, v101
	global_store_dwordx4 v[114:115], v[118:121], off
	s_cbranch_vccnz .LBB0_387
	v_mov_b32_e32 v114, v110
	v_mov_b32_e32 v110, v113
	v_mov_b32_e32 v113, v104
	v_mov_b32_e32 v115, v102
	v_mov_b32_e32 v102, v111
	v_mov_b32_e32 v111, v105
	v_pk_mul_f32 v[104:105], v[112:113], v[112:113]
	v_mov_b32_e32 v112, v109
	v_mov_b32_e32 v109, v100
	v_mov_b32_e32 v113, v101
	v_pk_mul_f32 v[100:101], v[108:109], v[108:109]
	v_mov_b32_e32 v108, v107
	v_mov_b32_e32 v107, v98
	v_pk_mul_f32 v[102:103], v[102:103], v[102:103]
	v_mov_b32_e32 v109, v99
	v_pk_mul_f32 v[98:99], v[106:107], v[106:107]
	v_pk_fma_f32 v[102:103], v[114:115], v[114:115], v[102:103]
	v_pk_fma_f32 v[104:105], v[110:111], v[110:111], v[104:105]
	v_pk_fma_f32 v[98:99], v[108:109], v[108:109], v[98:99]
	v_pk_fma_f32 v[100:101], v[112:113], v[112:113], v[100:101]
	v_pk_add_f32 v[102:103], v[102:103], v[104:105]
	v_pk_add_f32 v[98:99], v[100:101], v[98:99]
	s_nop 0
	v_pk_add_f32 v[98:99], v[102:103], v[98:99]
	s_nop 0
	v_add_f32_e32 v1, v98, v99
	v_and_b32_e32 v99, 64, v211
	v_xor_b32_e32 v98, 16, v211
	v_add_u32_e32 v99, 64, v99
	v_cmp_lt_i32_e32 vcc, v98, v99
	s_nop 1
	v_cndmask_b32_e32 v98, v211, v98, vcc
	v_lshlrev_b32_e32 v98, 2, v98
	ds_bpermute_b32 v98, v98, v1
	s_waitcnt lgkmcnt(0)
	v_add_f32_e32 v1, v1, v98
	v_xor_b32_e32 v98, 32, v211
	v_cmp_lt_i32_e32 vcc, v98, v99
	s_nop 1
	v_cndmask_b32_e32 v98, v211, v98, vcc
	v_lshlrev_b32_e32 v98, 2, v98
	ds_bpermute_b32 v98, v98, v1
	s_waitcnt lgkmcnt(0)
	v_add_f32_e32 v1, v1, v98
	v_cndmask_b32_e64 v116, v116, v1, s[4:5]
.LBB0_387:
	v_lshlrev_b64 v[102:103], 1, v[202:203]
	v_lshl_add_u64 v[104:105], s[14:15], 0, v[102:103]
	v_or_b32_e32 v102, 0x100, v102
	v_pk_fma_f32 v[96:97], v[96:97], 0.5, v[160:161] op_sel_hi:[1,0,1]
	v_pk_fma_f32 v[94:95], v[94:95], 0.5, v[158:159] op_sel_hi:[1,0,1]
	v_pk_fma_f32 v[92:93], v[92:93], 0.5, v[156:157] op_sel_hi:[1,0,1]
	v_pk_fma_f32 v[90:91], v[90:91], 0.5, v[154:155] op_sel_hi:[1,0,1]
	v_cvt_pk_bf16_f32 v98, v94, v95
	v_cvt_pk_bf16_f32 v99, v96, v97
	v_pk_fma_f32 v[88:89], v[88:89], 0.5, v[152:153] op_sel_hi:[1,0,1]
	v_cvt_pk_bf16_f32 v100, v90, v91
	v_cvt_pk_bf16_f32 v101, v92, v93
	v_pk_fma_f32 v[86:87], v[86:87], 0.5, v[150:151] op_sel_hi:[1,0,1]
	v_pk_fma_f32 v[84:85], v[84:85], 0.5, v[148:149] op_sel_hi:[1,0,1]
	v_pk_fma_f32 v[82:83], v[82:83], 0.5, v[146:147] op_sel_hi:[1,0,1]
	v_lshl_add_u64 v[102:103], s[14:15], 0, v[102:103]
	s_and_b64 vcc, exec, s[12:13]
	global_store_dwordx4 v[104:105], v[98:101], off
	s_nop 0
	s_nop 1
	v_cvt_pk_bf16_f32 v98, v86, v87
	v_cvt_pk_bf16_f32 v99, v88, v89
	v_cvt_pk_bf16_f32 v100, v82, v83
	v_cvt_pk_bf16_f32 v101, v84, v85
	global_store_dwordx4 v[102:103], v[98:101], off
	s_cbranch_vccnz .LBB0_389
	s_nop 0
	v_mov_b32_e32 v98, v94
	v_mov_b32_e32 v94, v97
	v_mov_b32_e32 v97, v88
	v_mov_b32_e32 v99, v86
	v_mov_b32_e32 v86, v95
	v_mov_b32_e32 v95, v89
	v_pk_mul_f32 v[88:89], v[96:97], v[96:97]
	v_mov_b32_e32 v96, v93
	v_mov_b32_e32 v93, v84
	v_mov_b32_e32 v97, v85
	v_pk_mul_f32 v[84:85], v[92:93], v[92:93]
	v_mov_b32_e32 v92, v91
	v_mov_b32_e32 v91, v82
	v_pk_mul_f32 v[86:87], v[86:87], v[86:87]
	v_mov_b32_e32 v93, v83
	v_pk_mul_f32 v[82:83], v[90:91], v[90:91]
	v_pk_fma_f32 v[86:87], v[98:99], v[98:99], v[86:87]
	v_pk_fma_f32 v[88:89], v[94:95], v[94:95], v[88:89]
	v_pk_fma_f32 v[82:83], v[92:93], v[92:93], v[82:83]
	v_pk_fma_f32 v[84:85], v[96:97], v[96:97], v[84:85]
	v_pk_add_f32 v[86:87], v[86:87], v[88:89]
	v_pk_add_f32 v[82:83], v[84:85], v[82:83]
	s_nop 0
	v_pk_add_f32 v[82:83], v[86:87], v[82:83]
	s_nop 0
	v_add_f32_e32 v1, v82, v83
	v_and_b32_e32 v83, 64, v211
	v_xor_b32_e32 v82, 16, v211
	v_add_u32_e32 v83, 64, v83
	v_cmp_lt_i32_e32 vcc, v82, v83
	s_nop 1
	v_cndmask_b32_e32 v82, v211, v82, vcc
	v_lshlrev_b32_e32 v82, 2, v82
	ds_bpermute_b32 v82, v82, v1
	s_waitcnt lgkmcnt(0)
	v_add_f32_e32 v1, v1, v82
	v_xor_b32_e32 v82, 32, v211
	v_cmp_lt_i32_e32 vcc, v82, v83
	s_nop 1
	v_cndmask_b32_e32 v82, v211, v82, vcc
	v_lshlrev_b32_e32 v82, 2, v82
	ds_bpermute_b32 v82, v82, v1
	s_waitcnt lgkmcnt(0)
	v_add_f32_e32 v1, v1, v82
	v_cndmask_b32_e64 v116, v116, v1, s[6:7]
.LBB0_389:
	v_lshlrev_b64 v[86:87], 1, v[200:201]
	v_or_b32_e32 v114, s56, v252
	v_lshl_add_u64 v[88:89], s[14:15], 0, v[86:87]
	v_or_b32_e32 v86, 0x100, v86
	v_pk_fma_f32 v[80:81], v[80:81], 0.5, v[144:145] op_sel_hi:[1,0,1]
	v_pk_fma_f32 v[78:79], v[78:79], 0.5, v[142:143] op_sel_hi:[1,0,1]
	v_pk_fma_f32 v[76:77], v[76:77], 0.5, v[140:141] op_sel_hi:[1,0,1]
	v_pk_fma_f32 v[74:75], v[74:75], 0.5, v[138:139] op_sel_hi:[1,0,1]
	v_cvt_pk_bf16_f32 v82, v78, v79
	v_cvt_pk_bf16_f32 v83, v80, v81
	v_pk_fma_f32 v[72:73], v[72:73], 0.5, v[136:137] op_sel_hi:[1,0,1]
	v_cvt_pk_bf16_f32 v84, v74, v75
	v_cvt_pk_bf16_f32 v85, v76, v77
	v_pk_fma_f32 v[70:71], v[70:71], 0.5, v[134:135] op_sel_hi:[1,0,1]
	v_pk_fma_f32 v[68:69], v[68:69], 0.5, v[132:133] op_sel_hi:[1,0,1]
	v_pk_fma_f32 v[66:67], v[66:67], 0.5, v[130:131] op_sel_hi:[1,0,1]
	v_lshl_add_u64 v[86:87], s[14:15], 0, v[86:87]
	s_and_b64 vcc, exec, s[12:13]
	v_ashrrev_i32_e32 v115, 31, v114
	global_store_dwordx4 v[88:89], v[82:85], off
	s_nop 0
	s_nop 1
	v_cvt_pk_bf16_f32 v82, v70, v71
	v_cvt_pk_bf16_f32 v83, v72, v73
	v_cvt_pk_bf16_f32 v84, v66, v67
	v_cvt_pk_bf16_f32 v85, v68, v69
	global_store_dwordx4 v[86:87], v[82:85], off
	s_cbranch_vccnz .LBB0_391
	v_mul_f32_e32 v1, v79, v79
	v_mul_f32_e32 v71, v71, v71
	v_mul_f32_e32 v66, v66, v66
	v_fmac_f32_e32 v1, v78, v78
	v_mul_f32_e32 v78, v80, v80
	v_mul_f32_e32 v76, v76, v76
	v_mul_f32_e32 v74, v74, v74
	v_fmac_f32_e32 v71, v70, v70
	v_mul_f32_e32 v70, v72, v72
	v_fmac_f32_e32 v66, v67, v67
	v_mul_f32_e32 v67, v68, v68
	v_fmac_f32_e32 v78, v81, v81
	v_fmac_f32_e32 v76, v77, v77
	v_fmac_f32_e32 v74, v75, v75
	v_fmac_f32_e32 v70, v73, v73
	v_fmac_f32_e32 v67, v69, v69
	v_add_f32_e32 v1, v1, v78
	v_add_f32_e32 v74, v76, v74
	v_add_f32_e32 v70, v71, v70
	v_add_f32_e32 v66, v67, v66
	v_add_f32_e32 v1, v1, v74
	v_add_f32_e32 v66, v70, v66
	v_and_b32_e32 v67, 64, v211
	v_add_f32_e32 v1, v1, v66
	v_xor_b32_e32 v66, 16, v211
	v_add_u32_e32 v67, 64, v67
	v_cmp_lt_i32_e32 vcc, v66, v67
	s_nop 1
	v_cndmask_b32_e32 v66, v211, v66, vcc
	v_lshlrev_b32_e32 v66, 2, v66
	ds_bpermute_b32 v66, v66, v1
	s_waitcnt lgkmcnt(0)
	v_add_f32_e32 v1, v1, v66
	v_xor_b32_e32 v66, 32, v211
	v_cmp_lt_i32_e32 vcc, v66, v67
	s_nop 1
	v_cndmask_b32_e32 v66, v211, v66, vcc
	v_lshlrev_b32_e32 v66, 2, v66
	ds_bpermute_b32 v66, v66, v1
	s_waitcnt lgkmcnt(0)
	v_add_f32_e32 v1, v1, v66
	v_cndmask_b32_e64 v1, v116, v1, s[8:9]
	v_lshl_add_u64 v[66:67], v[114:115], 2, s[26:27]
	global_atomic_add_f32 v[66:67], v1, off
.LBB0_391:
	v_add_u32_e32 v66, 0x80, v198
	v_ashrrev_i32_e32 v67, 31, v66
	v_lshlrev_b64 v[66:67], 11, v[66:67]
	v_lshl_add_u64 v[138:139], v[66:67], 0, v[196:197]
	v_lshl_add_u64 v[66:67], v[138:139], 2, s[68:69]
	global_load_dwordx4 v[122:125], v[66:67], off offset:16
	global_load_dwordx4 v[126:129], v[66:67], off
	global_load_dwordx4 v[130:133], v[66:67], off offset:528
	global_load_dwordx4 v[134:137], v[66:67], off offset:512
	v_add_u32_e32 v66, 0x90, v198
	v_ashrrev_i32_e32 v67, 31, v66
	v_lshlrev_b64 v[66:67], 11, v[66:67]
	v_lshl_add_u64 v[120:121], v[66:67], 0, v[196:197]
	v_lshl_add_u64 v[66:67], v[120:121], 2, s[68:69]
	global_load_dwordx4 v[106:109], v[66:67], off offset:16
	global_load_dwordx4 v[110:113], v[66:67], off
	global_load_dwordx4 v[98:101], v[66:67], off offset:528
	global_load_dwordx4 v[102:105], v[66:67], off offset:512
	v_add_u32_e32 v66, 0xa0, v198
	v_ashrrev_i32_e32 v67, 31, v66
	v_lshlrev_b64 v[66:67], 11, v[66:67]
	v_lshl_add_u64 v[118:119], v[66:67], 0, v[196:197]
	v_lshl_add_u64 v[66:67], v[118:119], 2, s[68:69]
	global_load_dwordx4 v[90:93], v[66:67], off offset:16
	global_load_dwordx4 v[94:97], v[66:67], off
	global_load_dwordx4 v[82:85], v[66:67], off offset:528
	global_load_dwordx4 v[86:89], v[66:67], off offset:512
	v_add_u32_e32 v66, 0xb0, v198
	v_ashrrev_i32_e32 v67, 31, v66
	v_lshlrev_b64 v[66:67], 11, v[66:67]
	v_lshl_add_u64 v[116:117], v[66:67], 0, v[196:197]
	v_lshl_add_u64 v[70:71], v[116:117], 2, s[68:69]
	global_load_dwordx4 v[74:77], v[70:71], off offset:16
	global_load_dwordx4 v[78:81], v[70:71], off
	global_load_dwordx4 v[66:69], v[70:71], off offset:528
	s_nop 0
	global_load_dwordx4 v[70:73], v[70:71], off offset:512
	v_lshlrev_b64 v[138:139], 1, v[138:139]
	v_lshl_add_u64 v[140:141], s[14:15], 0, v[138:139]
	v_or_b32_e32 v138, 0x100, v138
	v_lshl_add_u64 v[138:139], s[14:15], 0, v[138:139]
	s_and_b64 vcc, exec, s[12:13]
	s_waitcnt vmcnt(15)
	v_pk_fma_f32 v[60:61], v[60:61], 0.5, v[124:125] op_sel_hi:[1,0,1]
	s_waitcnt vmcnt(14)
	v_pk_fma_f32 v[64:65], v[64:65], 0.5, v[128:129] op_sel_hi:[1,0,1]
	v_pk_fma_f32 v[62:63], v[62:63], 0.5, v[126:127] op_sel_hi:[1,0,1]
	v_pk_fma_f32 v[58:59], v[58:59], 0.5, v[122:123] op_sel_hi:[1,0,1]
	s_waitcnt vmcnt(12)
	v_pk_fma_f32 v[56:57], v[56:57], 0.5, v[136:137] op_sel_hi:[1,0,1]
	v_pk_fma_f32 v[54:55], v[54:55], 0.5, v[134:135] op_sel_hi:[1,0,1]
	v_pk_fma_f32 v[52:53], v[52:53], 0.5, v[132:133] op_sel_hi:[1,0,1]
	v_pk_fma_f32 v[50:51], v[50:51], 0.5, v[130:131] op_sel_hi:[1,0,1]
	v_cvt_pk_bf16_f32 v122, v62, v63
	v_cvt_pk_bf16_f32 v123, v64, v65
	v_cvt_pk_bf16_f32 v124, v58, v59
	v_cvt_pk_bf16_f32 v125, v60, v61
	global_store_dwordx4 v[140:141], v[122:125], off
	s_nop 0
	s_nop 1
	v_cvt_pk_bf16_f32 v122, v54, v55
	v_cvt_pk_bf16_f32 v123, v56, v57
	v_cvt_pk_bf16_f32 v124, v50, v51
	v_cvt_pk_bf16_f32 v125, v52, v53
	global_store_dwordx4 v[138:139], v[122:125], off
	s_cbranch_vccnz .LBB0_393
	s_nop 0
	v_mov_b32_e32 v122, v62
	v_mov_b32_e32 v62, v65
	v_mov_b32_e32 v65, v56
	v_mov_b32_e32 v123, v54
	v_mov_b32_e32 v54, v63
	v_mov_b32_e32 v63, v57
	v_pk_mul_f32 v[56:57], v[64:65], v[64:65]
	v_mov_b32_e32 v64, v61
	v_mov_b32_e32 v61, v52
	v_mov_b32_e32 v65, v53
	v_pk_mul_f32 v[52:53], v[60:61], v[60:61]
	v_mov_b32_e32 v60, v59
	v_mov_b32_e32 v59, v50
	v_pk_mul_f32 v[54:55], v[54:55], v[54:55]
	v_mov_b32_e32 v61, v51
	v_pk_mul_f32 v[50:51], v[58:59], v[58:59]
	v_pk_fma_f32 v[54:55], v[122:123], v[122:123], v[54:55]
	v_pk_fma_f32 v[56:57], v[62:63], v[62:63], v[56:57]
	v_pk_fma_f32 v[50:51], v[60:61], v[60:61], v[50:51]
	v_pk_fma_f32 v[52:53], v[64:65], v[64:65], v[52:53]
	v_pk_add_f32 v[54:55], v[54:55], v[56:57]
	v_pk_add_f32 v[50:51], v[52:53], v[50:51]
	s_nop 0
	v_pk_add_f32 v[50:51], v[54:55], v[50:51]
	s_nop 0
	v_add_f32_e32 v1, v50, v51
	v_and_b32_e32 v51, 64, v211
	v_xor_b32_e32 v50, 16, v211
	v_add_u32_e32 v51, 64, v51
	v_cmp_lt_i32_e32 vcc, v50, v51
	s_nop 1
	v_cndmask_b32_e32 v50, v211, v50, vcc
	v_lshlrev_b32_e32 v50, 2, v50
	ds_bpermute_b32 v50, v50, v1
	s_waitcnt lgkmcnt(0)
	v_add_f32_e32 v1, v1, v50
	v_xor_b32_e32 v50, 32, v211
	v_cmp_lt_i32_e32 vcc, v50, v51
	s_nop 1
	v_cndmask_b32_e32 v50, v211, v50, vcc
	v_lshlrev_b32_e32 v50, 2, v50
	ds_bpermute_b32 v50, v50, v1
	s_waitcnt lgkmcnt(0)
	v_add_f32_e32 v1, v1, v50
	v_cndmask_b32_e64 v50, 0, v1, s[2:3]
	s_branch .LBB0_394

.LBB0_394:
	v_lshlrev_b64 v[56:57], 1, v[120:121]
	v_lshl_add_u64 v[58:59], s[14:15], 0, v[56:57]
	v_or_b32_e32 v56, 0x100, v56
	s_waitcnt vmcnt(12)
	v_pk_fma_f32 v[48:49], v[48:49], 0.5, v[112:113] op_sel_hi:[1,0,1]
	v_pk_fma_f32 v[46:47], v[46:47], 0.5, v[110:111] op_sel_hi:[1,0,1]
	v_pk_fma_f32 v[44:45], v[44:45], 0.5, v[108:109] op_sel_hi:[1,0,1]
	v_pk_fma_f32 v[42:43], v[42:43], 0.5, v[106:107] op_sel_hi:[1,0,1]
	v_cvt_pk_bf16_f32 v52, v46, v47
	v_cvt_pk_bf16_f32 v53, v48, v49
	s_waitcnt vmcnt(10)
	v_pk_fma_f32 v[40:41], v[40:41], 0.5, v[104:105] op_sel_hi:[1,0,1]
	v_cvt_pk_bf16_f32 v54, v42, v43
	v_cvt_pk_bf16_f32 v55, v44, v45
	v_pk_fma_f32 v[38:39], v[38:39], 0.5, v[102:103] op_sel_hi:[1,0,1]
	v_pk_fma_f32 v[36:37], v[36:37], 0.5, v[100:101] op_sel_hi:[1,0,1]
	v_pk_fma_f32 v[34:35], v[34:35], 0.5, v[98:99] op_sel_hi:[1,0,1]
	v_lshl_add_u64 v[56:57], s[14:15], 0, v[56:57]
	s_and_b64 vcc, exec, s[12:13]
	global_store_dwordx4 v[58:59], v[52:55], off
	s_nop 0
	s_nop 1
	v_cvt_pk_bf16_f32 v52, v38, v39
	v_cvt_pk_bf16_f32 v53, v40, v41
	v_cvt_pk_bf16_f32 v54, v34, v35
	v_cvt_pk_bf16_f32 v55, v36, v37
	global_store_dwordx4 v[56:57], v[52:55], off
	s_cbranch_vccnz .LBB0_396
	s_nop 0
	v_mov_b32_e32 v52, v46
	v_mov_b32_e32 v46, v49
	v_mov_b32_e32 v49, v40
	v_mov_b32_e32 v53, v38
	v_mov_b32_e32 v38, v47
	v_mov_b32_e32 v47, v41
	v_pk_mul_f32 v[40:41], v[48:49], v[48:49]
	v_mov_b32_e32 v48, v45
	v_mov_b32_e32 v45, v36
	v_mov_b32_e32 v49, v37
	v_pk_mul_f32 v[36:37], v[44:45], v[44:45]
	v_mov_b32_e32 v44, v43
	v_mov_b32_e32 v43, v34
	v_pk_mul_f32 v[38:39], v[38:39], v[38:39]
	v_mov_b32_e32 v45, v35
	v_pk_mul_f32 v[34:35], v[42:43], v[42:43]
	v_pk_fma_f32 v[38:39], v[52:53], v[52:53], v[38:39]
	v_pk_fma_f32 v[40:41], v[46:47], v[46:47], v[40:41]
	v_pk_fma_f32 v[34:35], v[44:45], v[44:45], v[34:35]
	v_pk_fma_f32 v[36:37], v[48:49], v[48:49], v[36:37]
	v_pk_add_f32 v[38:39], v[38:39], v[40:41]
	v_pk_add_f32 v[34:35], v[36:37], v[34:35]
	s_nop 0
	v_pk_add_f32 v[34:35], v[38:39], v[34:35]
	s_nop 0
	v_add_f32_e32 v1, v34, v35
	v_and_b32_e32 v35, 64, v211
	v_xor_b32_e32 v34, 16, v211
	v_add_u32_e32 v35, 64, v35
	v_cmp_lt_i32_e32 vcc, v34, v35
	s_nop 1
	v_cndmask_b32_e32 v34, v211, v34, vcc
	v_lshlrev_b32_e32 v34, 2, v34
	ds_bpermute_b32 v34, v34, v1
	s_waitcnt lgkmcnt(0)
	v_add_f32_e32 v1, v1, v34
	v_xor_b32_e32 v34, 32, v211
	v_cmp_lt_i32_e32 vcc, v34, v35
	s_nop 1
	v_cndmask_b32_e32 v34, v211, v34, vcc
	v_lshlrev_b32_e32 v34, 2, v34
	ds_bpermute_b32 v34, v34, v1
	s_waitcnt lgkmcnt(0)
	v_add_f32_e32 v1, v1, v34
	v_cndmask_b32_e64 v50, v50, v1, s[4:5]
.LBB0_396:
	v_lshlrev_b64 v[38:39], 1, v[118:119]
	v_lshl_add_u64 v[40:41], s[14:15], 0, v[38:39]
	v_or_b32_e32 v38, 0x100, v38
	s_waitcnt vmcnt(10)
	v_pk_fma_f32 v[32:33], v[32:33], 0.5, v[96:97] op_sel_hi:[1,0,1]
	v_pk_fma_f32 v[30:31], v[30:31], 0.5, v[94:95] op_sel_hi:[1,0,1]
	v_pk_fma_f32 v[28:29], v[28:29], 0.5, v[92:93] op_sel_hi:[1,0,1]
	v_pk_fma_f32 v[26:27], v[26:27], 0.5, v[90:91] op_sel_hi:[1,0,1]
	v_cvt_pk_bf16_f32 v34, v30, v31
	v_cvt_pk_bf16_f32 v35, v32, v33
	s_waitcnt vmcnt(8)
	v_pk_fma_f32 v[24:25], v[24:25], 0.5, v[88:89] op_sel_hi:[1,0,1]
	v_cvt_pk_bf16_f32 v36, v26, v27
	v_cvt_pk_bf16_f32 v37, v28, v29
	v_pk_fma_f32 v[22:23], v[22:23], 0.5, v[86:87] op_sel_hi:[1,0,1]
	v_pk_fma_f32 v[20:21], v[20:21], 0.5, v[84:85] op_sel_hi:[1,0,1]
	v_pk_fma_f32 v[18:19], v[18:19], 0.5, v[82:83] op_sel_hi:[1,0,1]
	v_lshl_add_u64 v[38:39], s[14:15], 0, v[38:39]
	s_and_b64 vcc, exec, s[12:13]
	global_store_dwordx4 v[40:41], v[34:37], off
	s_nop 0
	s_nop 1
	v_cvt_pk_bf16_f32 v34, v22, v23
	v_cvt_pk_bf16_f32 v35, v24, v25
	v_cvt_pk_bf16_f32 v36, v18, v19
	v_cvt_pk_bf16_f32 v37, v20, v21
	global_store_dwordx4 v[38:39], v[34:37], off
	s_cbranch_vccnz .LBB0_398
	s_nop 0
	v_mov_b32_e32 v34, v30
	v_mov_b32_e32 v30, v33
	v_mov_b32_e32 v33, v24
	v_mov_b32_e32 v35, v22
	v_mov_b32_e32 v22, v31
	v_mov_b32_e32 v31, v25
	v_pk_mul_f32 v[24:25], v[32:33], v[32:33]
	v_mov_b32_e32 v32, v29
	v_mov_b32_e32 v29, v20
	v_mov_b32_e32 v33, v21
	v_pk_mul_f32 v[20:21], v[28:29], v[28:29]
	v_mov_b32_e32 v28, v27
	v_mov_b32_e32 v27, v18
	v_pk_mul_f32 v[22:23], v[22:23], v[22:23]
	v_mov_b32_e32 v29, v19
	v_pk_mul_f32 v[18:19], v[26:27], v[26:27]
	v_pk_fma_f32 v[22:23], v[34:35], v[34:35], v[22:23]
	v_pk_fma_f32 v[24:25], v[30:31], v[30:31], v[24:25]
	v_pk_fma_f32 v[18:19], v[28:29], v[28:29], v[18:19]
	v_pk_fma_f32 v[20:21], v[32:33], v[32:33], v[20:21]
	v_pk_add_f32 v[22:23], v[22:23], v[24:25]
	v_pk_add_f32 v[18:19], v[20:21], v[18:19]
	s_nop 0
	v_pk_add_f32 v[18:19], v[22:23], v[18:19]
	s_nop 0
	v_add_f32_e32 v1, v18, v19
	v_and_b32_e32 v19, 64, v211
	v_xor_b32_e32 v18, 16, v211
	v_add_u32_e32 v19, 64, v19
	v_cmp_lt_i32_e32 vcc, v18, v19
	s_nop 1
	v_cndmask_b32_e32 v18, v211, v18, vcc
	v_lshlrev_b32_e32 v18, 2, v18
	ds_bpermute_b32 v18, v18, v1
	s_waitcnt lgkmcnt(0)
	v_add_f32_e32 v1, v1, v18
	v_xor_b32_e32 v18, 32, v211
	v_cmp_lt_i32_e32 vcc, v18, v19
	s_nop 1
	v_cndmask_b32_e32 v18, v211, v18, vcc
	v_lshlrev_b32_e32 v18, 2, v18
	ds_bpermute_b32 v18, v18, v1
	s_waitcnt lgkmcnt(0)
	v_add_f32_e32 v1, v1, v18
	v_cndmask_b32_e64 v50, v50, v1, s[6:7]
.LBB0_398:
	v_lshlrev_b64 v[22:23], 1, v[116:117]
	v_lshl_add_u64 v[24:25], s[14:15], 0, v[22:23]
	v_or_b32_e32 v22, 0x100, v22
	s_waitcnt vmcnt(8)
	v_pk_fma_f32 v[16:17], v[16:17], 0.5, v[80:81] op_sel_hi:[1,0,1]
	v_pk_fma_f32 v[14:15], v[14:15], 0.5, v[78:79] op_sel_hi:[1,0,1]
	v_pk_fma_f32 v[12:13], v[12:13], 0.5, v[76:77] op_sel_hi:[1,0,1]
	v_pk_fma_f32 v[10:11], v[10:11], 0.5, v[74:75] op_sel_hi:[1,0,1]
	v_cvt_pk_bf16_f32 v18, v14, v15
	v_cvt_pk_bf16_f32 v19, v16, v17
	s_waitcnt vmcnt(6)
	v_pk_fma_f32 v[8:9], v[8:9], 0.5, v[72:73] op_sel_hi:[1,0,1]
	v_cvt_pk_bf16_f32 v20, v10, v11
	v_cvt_pk_bf16_f32 v21, v12, v13
	v_pk_fma_f32 v[6:7], v[6:7], 0.5, v[70:71] op_sel_hi:[1,0,1]
	v_pk_fma_f32 v[4:5], v[4:5], 0.5, v[68:69] op_sel_hi:[1,0,1]
	v_pk_fma_f32 v[2:3], v[2:3], 0.5, v[66:67] op_sel_hi:[1,0,1]
	v_lshl_add_u64 v[22:23], s[14:15], 0, v[22:23]
	s_and_b64 vcc, exec, s[12:13]
	global_store_dwordx4 v[24:25], v[18:21], off
	s_nop 0
	s_nop 1
	v_cvt_pk_bf16_f32 v18, v6, v7
	v_cvt_pk_bf16_f32 v19, v8, v9
	v_cvt_pk_bf16_f32 v20, v2, v3
	v_cvt_pk_bf16_f32 v21, v4, v5
	global_store_dwordx4 v[22:23], v[18:21], off
	s_cbranch_vccnz .LBB0_400
	v_mul_f32_e32 v1, v15, v15
	v_mul_f32_e32 v7, v7, v7
	v_mul_f32_e32 v2, v2, v2
	v_fmac_f32_e32 v1, v14, v14
	v_mul_f32_e32 v14, v16, v16
	v_mul_f32_e32 v12, v12, v12
	v_mul_f32_e32 v10, v10, v10
	v_fmac_f32_e32 v7, v6, v6
	v_mul_f32_e32 v6, v8, v8
	v_fmac_f32_e32 v2, v3, v3
	v_mul_f32_e32 v3, v4, v4
	v_fmac_f32_e32 v14, v17, v17
	v_fmac_f32_e32 v12, v13, v13
	v_fmac_f32_e32 v10, v11, v11
	v_fmac_f32_e32 v6, v9, v9
	v_fmac_f32_e32 v3, v5, v5
	v_add_f32_e32 v1, v1, v14
	v_add_f32_e32 v10, v12, v10
	v_add_f32_e32 v6, v7, v6
	v_add_f32_e32 v2, v3, v2
	v_add_f32_e32 v1, v1, v10
	v_add_f32_e32 v2, v6, v2
	v_and_b32_e32 v3, 64, v211
	v_add_f32_e32 v1, v1, v2
	v_xor_b32_e32 v2, 16, v211
	v_add_u32_e32 v3, 64, v3
	v_cmp_lt_i32_e32 vcc, v2, v3
	s_nop 1
	v_cndmask_b32_e32 v2, v211, v2, vcc
	v_lshlrev_b32_e32 v2, 2, v2
	ds_bpermute_b32 v2, v2, v1
	s_waitcnt lgkmcnt(0)
	v_add_f32_e32 v1, v1, v2
	v_xor_b32_e32 v2, 32, v211
	v_cmp_lt_i32_e32 vcc, v2, v3
	s_nop 1
	v_cndmask_b32_e32 v2, v211, v2, vcc
	v_lshlrev_b32_e32 v2, 2, v2
	ds_bpermute_b32 v2, v2, v1
	s_waitcnt lgkmcnt(0)
	v_add_f32_e32 v1, v1, v2
	v_cndmask_b32_e64 v1, v50, v1, s[8:9]
	v_lshl_add_u64 v[2:3], v[114:115], 2, s[26:27]
	global_atomic_add_f32 v[2:3], v1, off offset:512

.LBB0_704:
	v_lshl_add_u32 v144, s52, 8, v138
	v_lshl_or_b32 v134, s74, 8, v140
	v_ashrrev_i32_e32 v135, 31, v134
	v_ashrrev_i32_e32 v145, 31, v144
	v_lshl_add_u64 v[146:147], v[134:135], 1, s[2:3]
	v_lshlrev_b64 v[134:135], 10, v[144:145]
	v_lshl_add_u64 v[134:135], v[146:147], 0, v[134:135]
	v_pk_add_f32 v[128:129], v[128:129], 0 op_sel_hi:[1,0]
	v_pk_add_f32 v[126:127], v[126:127], 0 op_sel_hi:[1,0]
	v_pk_add_f32 v[148:149], v[124:125], 0 op_sel_hi:[1,0]
	v_pk_add_f32 v[124:125], v[122:123], 0 op_sel_hi:[1,0]
	v_cvt_pk_bf16_f32 v122, v126, v127
	v_cvt_pk_bf16_f32 v123, v128, v129
	v_pk_add_f32 v[118:119], v[118:119], 0 op_sel_hi:[1,0]
	v_cvt_pk_bf16_f32 v124, v124, v125
	v_cvt_pk_bf16_f32 v125, v148, v149
	global_store_dwordx4 v[134:135], v[122:125], off
	v_pk_add_f32 v[120:121], v[120:121], 0 op_sel_hi:[1,0]
	v_pk_add_f32 v[114:115], v[114:115], 0 op_sel_hi:[1,0]
	v_pk_add_f32 v[122:123], v[112:113], 0 op_sel_hi:[1,0]
	v_pk_add_f32 v[112:113], v[110:111], 0 op_sel_hi:[1,0]
	v_cvt_pk_bf16_f32 v110, v118, v119
	v_cvt_pk_bf16_f32 v111, v120, v121
	v_pk_add_f32 v[102:103], v[102:103], 0 op_sel_hi:[1,0]
	v_cvt_pk_bf16_f32 v112, v112, v113
	v_cvt_pk_bf16_f32 v113, v122, v123
	global_store_dwordx4 v[134:135], v[110:113], off offset:256
	v_pk_add_f32 v[104:105], v[104:105], 0 op_sel_hi:[1,0]
	v_pk_add_f32 v[98:99], v[98:99], 0 op_sel_hi:[1,0]
	v_or_b32_e32 v110, 16, v144
	v_ashrrev_i32_e32 v111, 31, v110
	v_lshlrev_b64 v[110:111], 10, v[110:111]
	v_lshl_add_u64 v[110:111], v[146:147], 0, v[110:111]
	v_pk_add_f32 v[112:113], v[116:117], 0 op_sel_hi:[1,0]
	v_pk_add_f32 v[116:117], v[108:109], 0 op_sel_hi:[1,0]
	v_pk_add_f32 v[108:109], v[106:107], 0 op_sel_hi:[1,0]
	v_cvt_pk_bf16_f32 v106, v114, v115
	v_cvt_pk_bf16_f32 v107, v112, v113
	v_pk_add_f32 v[86:87], v[86:87], 0 op_sel_hi:[1,0]
	v_cvt_pk_bf16_f32 v108, v108, v109
	v_cvt_pk_bf16_f32 v109, v116, v117
	global_store_dwordx4 v[110:111], v[106:109], off
	v_pk_add_f32 v[88:89], v[88:89], 0 op_sel_hi:[1,0]
	v_pk_add_f32 v[82:83], v[82:83], 0 op_sel_hi:[1,0]
	v_pk_add_f32 v[106:107], v[96:97], 0 op_sel_hi:[1,0]
	v_pk_add_f32 v[96:97], v[94:95], 0 op_sel_hi:[1,0]
	v_cvt_pk_bf16_f32 v94, v102, v103
	v_cvt_pk_bf16_f32 v95, v104, v105
	v_pk_add_f32 v[72:73], v[72:73], 0 op_sel_hi:[1,0]
	v_cvt_pk_bf16_f32 v96, v96, v97
	v_cvt_pk_bf16_f32 v97, v106, v107
	global_store_dwordx4 v[110:111], v[94:97], off offset:256
	v_pk_add_f32 v[70:71], v[70:71], 0 op_sel_hi:[1,0]
	v_pk_add_f32 v[62:63], v[62:63], 0 op_sel_hi:[1,0]
	v_or_b32_e32 v94, 32, v144
	v_ashrrev_i32_e32 v95, 31, v94
	v_lshlrev_b64 v[94:95], 10, v[94:95]
	v_lshl_add_u64 v[94:95], v[146:147], 0, v[94:95]
	v_pk_add_f32 v[96:97], v[100:101], 0 op_sel_hi:[1,0]
	v_pk_add_f32 v[100:101], v[92:93], 0 op_sel_hi:[1,0]
	v_pk_add_f32 v[92:93], v[90:91], 0 op_sel_hi:[1,0]
	v_cvt_pk_bf16_f32 v90, v98, v99
	v_cvt_pk_bf16_f32 v91, v96, v97
	v_pk_add_f32 v[64:65], v[64:65], 0 op_sel_hi:[1,0]
	v_cvt_pk_bf16_f32 v92, v92, v93
	v_cvt_pk_bf16_f32 v93, v100, v101
	global_store_dwordx4 v[94:95], v[90:93], off
	v_pk_add_f32 v[56:57], v[56:57], 0 op_sel_hi:[1,0]
	v_pk_add_f32 v[54:55], v[54:55], 0 op_sel_hi:[1,0]
	v_pk_add_f32 v[90:91], v[80:81], 0 op_sel_hi:[1,0]
	v_pk_add_f32 v[80:81], v[78:79], 0 op_sel_hi:[1,0]
	v_cvt_pk_bf16_f32 v78, v86, v87
	v_cvt_pk_bf16_f32 v79, v88, v89
	v_pk_add_f32 v[50:51], v[50:51], 0 op_sel_hi:[1,0]
	v_cvt_pk_bf16_f32 v80, v80, v81
	v_cvt_pk_bf16_f32 v81, v90, v91
	global_store_dwordx4 v[94:95], v[78:81], off offset:256
	v_pk_add_f32 v[40:41], v[40:41], 0 op_sel_hi:[1,0]
	v_pk_add_f32 v[38:39], v[38:39], 0 op_sel_hi:[1,0]
	v_or_b32_e32 v78, 48, v144
	v_ashrrev_i32_e32 v79, 31, v78
	v_lshlrev_b64 v[78:79], 10, v[78:79]
	v_lshl_add_u64 v[78:79], v[146:147], 0, v[78:79]
	v_pk_add_f32 v[80:81], v[84:85], 0 op_sel_hi:[1,0]
	v_pk_add_f32 v[84:85], v[76:77], 0 op_sel_hi:[1,0]
	v_pk_add_f32 v[76:77], v[74:75], 0 op_sel_hi:[1,0]
	v_cvt_pk_bf16_f32 v74, v82, v83
	v_cvt_pk_bf16_f32 v75, v80, v81
	v_pk_add_f32 v[34:35], v[34:35], 0 op_sel_hi:[1,0]
	v_cvt_pk_bf16_f32 v76, v76, v77
	v_cvt_pk_bf16_f32 v77, v84, v85
	global_store_dwordx4 v[78:79], v[74:77], off
	v_pk_add_f32 v[24:25], v[24:25], 0 op_sel_hi:[1,0]
	v_pk_add_f32 v[22:23], v[22:23], 0 op_sel_hi:[1,0]
	v_pk_add_f32 v[74:75], v[68:69], 0 op_sel_hi:[1,0]
	v_pk_add_f32 v[68:69], v[66:67], 0 op_sel_hi:[1,0]
	v_cvt_pk_bf16_f32 v66, v70, v71
	v_cvt_pk_bf16_f32 v67, v72, v73
	v_pk_add_f32 v[18:19], v[18:19], 0 op_sel_hi:[1,0]
	v_cvt_pk_bf16_f32 v68, v68, v69
	v_cvt_pk_bf16_f32 v69, v74, v75
	global_store_dwordx4 v[78:79], v[66:69], off offset:256
	v_pk_add_f32 v[8:9], v[8:9], 0 op_sel_hi:[1,0]
	v_pk_add_f32 v[6:7], v[6:7], 0 op_sel_hi:[1,0]
	v_pk_add_f32 v[68:69], v[60:61], 0 op_sel_hi:[1,0]
	v_pk_add_f32 v[60:61], v[58:59], 0 op_sel_hi:[1,0]
	v_cvt_pk_bf16_f32 v58, v62, v63
	v_add_co_u32_e32 v62, vcc, s70, v134
	v_cvt_pk_bf16_f32 v59, v64, v65
	v_cvt_pk_bf16_f32 v60, v60, v61
	v_cvt_pk_bf16_f32 v61, v68, v69
	v_lshl_add_u64 v[66:67], v[134:135], 0, s[8:9]
	s_nop 0
	v_addc_co_u32_e32 v63, vcc, 0, v135, vcc
	global_store_dwordx4 v[62:63], v[58:61], off
	s_nop 0
	s_nop 1
	v_pk_add_f32 v[58:59], v[48:49], 0 op_sel_hi:[1,0]
	v_pk_add_f32 v[48:49], v[46:47], 0 op_sel_hi:[1,0]
	v_cvt_pk_bf16_f32 v46, v54, v55
	v_cvt_pk_bf16_f32 v47, v56, v57
	s_nop 0
	v_cvt_pk_bf16_f32 v48, v48, v49
	v_cvt_pk_bf16_f32 v49, v58, v59
	global_store_dwordx4 v[66:67], v[46:49], off offset:256
	s_nop 0
	s_nop 1
	v_pk_add_f32 v[48:49], v[52:53], 0 op_sel_hi:[1,0]
	v_pk_add_f32 v[52:53], v[44:45], 0 op_sel_hi:[1,0]
	v_pk_add_f32 v[44:45], v[42:43], 0 op_sel_hi:[1,0]
	v_cvt_pk_bf16_f32 v42, v50, v51
	v_cvt_pk_bf16_f32 v43, v48, v49
	v_add_co_u32_e32 v48, vcc, s71, v134
	v_cvt_pk_bf16_f32 v44, v44, v45
	v_cvt_pk_bf16_f32 v45, v52, v53
	v_lshl_add_u64 v[46:47], v[134:135], 0, s[10:11]
	s_nop 0
	v_addc_co_u32_e32 v49, vcc, 0, v135, vcc
	global_store_dwordx4 v[48:49], v[42:45], off
	s_nop 0
	s_nop 1
	v_pk_add_f32 v[42:43], v[32:33], 0 op_sel_hi:[1,0]
	v_pk_add_f32 v[32:33], v[30:31], 0 op_sel_hi:[1,0]
	v_cvt_pk_bf16_f32 v30, v38, v39
	v_cvt_pk_bf16_f32 v31, v40, v41
	s_nop 0
	v_cvt_pk_bf16_f32 v32, v32, v33
	v_cvt_pk_bf16_f32 v33, v42, v43
	global_store_dwordx4 v[46:47], v[30:33], off offset:256
	s_nop 0
	s_nop 1
	v_pk_add_f32 v[32:33], v[36:37], 0 op_sel_hi:[1,0]
	v_pk_add_f32 v[36:37], v[28:29], 0 op_sel_hi:[1,0]
	v_pk_add_f32 v[28:29], v[26:27], 0 op_sel_hi:[1,0]
	v_cvt_pk_bf16_f32 v26, v34, v35
	v_cvt_pk_bf16_f32 v27, v32, v33
	v_add_co_u32_e32 v32, vcc, s72, v134
	v_cvt_pk_bf16_f32 v28, v28, v29
	v_cvt_pk_bf16_f32 v29, v36, v37
	v_lshl_add_u64 v[30:31], v[134:135], 0, s[12:13]
	s_nop 0
	v_addc_co_u32_e32 v33, vcc, 0, v135, vcc
	global_store_dwordx4 v[32:33], v[26:29], off
	s_nop 0
	s_nop 1
	v_pk_add_f32 v[26:27], v[16:17], 0 op_sel_hi:[1,0]
	v_pk_add_f32 v[16:17], v[14:15], 0 op_sel_hi:[1,0]
	v_cvt_pk_bf16_f32 v14, v22, v23
	v_cvt_pk_bf16_f32 v15, v24, v25
	s_nop 0
	v_cvt_pk_bf16_f32 v16, v16, v17
	v_cvt_pk_bf16_f32 v17, v26, v27
	global_store_dwordx4 v[30:31], v[14:17], off offset:256
	s_nop 0
	s_nop 1
	v_pk_add_f32 v[16:17], v[20:21], 0 op_sel_hi:[1,0]
	v_pk_add_f32 v[20:21], v[12:13], 0 op_sel_hi:[1,0]
	v_pk_add_f32 v[12:13], v[10:11], 0 op_sel_hi:[1,0]
	v_cvt_pk_bf16_f32 v10, v18, v19
	v_cvt_pk_bf16_f32 v11, v16, v17
	v_add_co_u32_e32 v16, vcc, s73, v134
	v_lshl_add_u64 v[14:15], v[134:135], 0, s[14:15]
	s_nop 0
	v_addc_co_u32_e32 v17, vcc, 0, v135, vcc
	v_cvt_pk_bf16_f32 v12, v12, v13
	v_cvt_pk_bf16_f32 v13, v20, v21
	global_store_dwordx4 v[16:17], v[10:13], off
	s_andn2_b64 vcc, exec, s[16:17]
	s_mov_b64 s[16:17], -1
	v_pk_add_f32 v[10:11], v[4:5], 0 op_sel_hi:[1,0]
	v_pk_add_f32 v[4:5], v[2:3], 0 op_sel_hi:[1,0]
	v_cvt_pk_bf16_f32 v2, v6, v7
	v_cvt_pk_bf16_f32 v3, v8, v9
	s_nop 0
	v_cvt_pk_bf16_f32 v4, v4, v5
	v_cvt_pk_bf16_f32 v5, v10, v11
	global_store_dwordx4 v[14:15], v[2:5], off offset:256
	s_cbranch_vccnz .LBB0_693
	s_andn2_b64 vcc, exec, s[0:1]
	s_cbranch_vccnz .LBB0_692
	s_barrier
	s_branch .LBB0_692

.LBB0_728:
	v_lshl_add_u32 v142, s52, 8, v138
	v_lshl_or_b32 v134, s75, 8, v137
	v_ashrrev_i32_e32 v135, 31, v134
	v_ashrrev_i32_e32 v143, 31, v142
	v_lshl_add_u64 v[144:145], v[134:135], 1, s[2:3]
	v_lshlrev_b64 v[134:135], 13, v[142:143]
	v_lshl_add_u64 v[134:135], v[144:145], 0, v[134:135]
	v_pk_add_f32 v[128:129], v[128:129], 0 op_sel_hi:[1,0]
	v_pk_add_f32 v[126:127], v[126:127], 0 op_sel_hi:[1,0]
	v_pk_add_f32 v[146:147], v[124:125], 0 op_sel_hi:[1,0]
	v_pk_add_f32 v[124:125], v[122:123], 0 op_sel_hi:[1,0]
	v_cvt_pk_bf16_f32 v122, v126, v127
	v_cvt_pk_bf16_f32 v123, v128, v129
	v_pk_add_f32 v[118:119], v[118:119], 0 op_sel_hi:[1,0]
	v_cvt_pk_bf16_f32 v124, v124, v125
	v_cvt_pk_bf16_f32 v125, v146, v147
	global_store_dwordx4 v[134:135], v[122:125], off
	v_pk_add_f32 v[120:121], v[120:121], 0 op_sel_hi:[1,0]
	v_pk_add_f32 v[114:115], v[114:115], 0 op_sel_hi:[1,0]
	v_pk_add_f32 v[122:123], v[112:113], 0 op_sel_hi:[1,0]
	v_pk_add_f32 v[112:113], v[110:111], 0 op_sel_hi:[1,0]
	v_cvt_pk_bf16_f32 v110, v118, v119
	v_cvt_pk_bf16_f32 v111, v120, v121
	v_pk_add_f32 v[102:103], v[102:103], 0 op_sel_hi:[1,0]
	v_cvt_pk_bf16_f32 v112, v112, v113
	v_cvt_pk_bf16_f32 v113, v122, v123
	global_store_dwordx4 v[134:135], v[110:113], off offset:256
	v_pk_add_f32 v[104:105], v[104:105], 0 op_sel_hi:[1,0]
	v_pk_add_f32 v[98:99], v[98:99], 0 op_sel_hi:[1,0]
	v_or_b32_e32 v110, 16, v142
	v_ashrrev_i32_e32 v111, 31, v110
	v_lshlrev_b64 v[110:111], 13, v[110:111]
	v_lshl_add_u64 v[110:111], v[144:145], 0, v[110:111]
	v_pk_add_f32 v[112:113], v[116:117], 0 op_sel_hi:[1,0]
	v_pk_add_f32 v[116:117], v[108:109], 0 op_sel_hi:[1,0]
	v_pk_add_f32 v[108:109], v[106:107], 0 op_sel_hi:[1,0]
	v_cvt_pk_bf16_f32 v106, v114, v115
	v_cvt_pk_bf16_f32 v107, v112, v113
	v_pk_add_f32 v[86:87], v[86:87], 0 op_sel_hi:[1,0]
	v_cvt_pk_bf16_f32 v108, v108, v109
	v_cvt_pk_bf16_f32 v109, v116, v117
	global_store_dwordx4 v[110:111], v[106:109], off
	v_pk_add_f32 v[88:89], v[88:89], 0 op_sel_hi:[1,0]
	v_pk_add_f32 v[82:83], v[82:83], 0 op_sel_hi:[1,0]
	v_pk_add_f32 v[106:107], v[96:97], 0 op_sel_hi:[1,0]
	v_pk_add_f32 v[96:97], v[94:95], 0 op_sel_hi:[1,0]
	v_cvt_pk_bf16_f32 v94, v102, v103
	v_cvt_pk_bf16_f32 v95, v104, v105
	v_pk_add_f32 v[72:73], v[72:73], 0 op_sel_hi:[1,0]
	v_cvt_pk_bf16_f32 v96, v96, v97
	v_cvt_pk_bf16_f32 v97, v106, v107
	global_store_dwordx4 v[110:111], v[94:97], off offset:256
	v_pk_add_f32 v[70:71], v[70:71], 0 op_sel_hi:[1,0]
	v_pk_add_f32 v[62:63], v[62:63], 0 op_sel_hi:[1,0]
	v_or_b32_e32 v94, 32, v142
	v_ashrrev_i32_e32 v95, 31, v94
	v_lshlrev_b64 v[94:95], 13, v[94:95]
	v_lshl_add_u64 v[94:95], v[144:145], 0, v[94:95]
	v_pk_add_f32 v[96:97], v[100:101], 0 op_sel_hi:[1,0]
	v_pk_add_f32 v[100:101], v[92:93], 0 op_sel_hi:[1,0]
	v_pk_add_f32 v[92:93], v[90:91], 0 op_sel_hi:[1,0]
	v_cvt_pk_bf16_f32 v90, v98, v99
	v_cvt_pk_bf16_f32 v91, v96, v97
	v_pk_add_f32 v[64:65], v[64:65], 0 op_sel_hi:[1,0]
	v_cvt_pk_bf16_f32 v92, v92, v93
	v_cvt_pk_bf16_f32 v93, v100, v101
	global_store_dwordx4 v[94:95], v[90:93], off
	v_pk_add_f32 v[56:57], v[56:57], 0 op_sel_hi:[1,0]
	v_pk_add_f32 v[54:55], v[54:55], 0 op_sel_hi:[1,0]
	v_pk_add_f32 v[90:91], v[80:81], 0 op_sel_hi:[1,0]
	v_pk_add_f32 v[80:81], v[78:79], 0 op_sel_hi:[1,0]
	v_cvt_pk_bf16_f32 v78, v86, v87
	v_cvt_pk_bf16_f32 v79, v88, v89
	v_pk_add_f32 v[50:51], v[50:51], 0 op_sel_hi:[1,0]
	v_cvt_pk_bf16_f32 v80, v80, v81
	v_cvt_pk_bf16_f32 v81, v90, v91
	global_store_dwordx4 v[94:95], v[78:81], off offset:256
	v_pk_add_f32 v[40:41], v[40:41], 0 op_sel_hi:[1,0]
	v_pk_add_f32 v[38:39], v[38:39], 0 op_sel_hi:[1,0]
	v_or_b32_e32 v78, 48, v142
	v_ashrrev_i32_e32 v79, 31, v78
	v_lshlrev_b64 v[78:79], 13, v[78:79]
	v_lshl_add_u64 v[78:79], v[144:145], 0, v[78:79]
	v_pk_add_f32 v[80:81], v[84:85], 0 op_sel_hi:[1,0]
	v_pk_add_f32 v[84:85], v[76:77], 0 op_sel_hi:[1,0]
	v_pk_add_f32 v[76:77], v[74:75], 0 op_sel_hi:[1,0]
	v_cvt_pk_bf16_f32 v74, v82, v83
	v_cvt_pk_bf16_f32 v75, v80, v81
	v_pk_add_f32 v[34:35], v[34:35], 0 op_sel_hi:[1,0]
	v_cvt_pk_bf16_f32 v76, v76, v77
	v_cvt_pk_bf16_f32 v77, v84, v85
	global_store_dwordx4 v[78:79], v[74:77], off
	v_pk_add_f32 v[24:25], v[24:25], 0 op_sel_hi:[1,0]
	v_pk_add_f32 v[22:23], v[22:23], 0 op_sel_hi:[1,0]
	v_pk_add_f32 v[74:75], v[68:69], 0 op_sel_hi:[1,0]
	v_pk_add_f32 v[68:69], v[66:67], 0 op_sel_hi:[1,0]
	v_cvt_pk_bf16_f32 v66, v70, v71
	v_cvt_pk_bf16_f32 v67, v72, v73
	v_pk_add_f32 v[18:19], v[18:19], 0 op_sel_hi:[1,0]
	v_cvt_pk_bf16_f32 v68, v68, v69
	v_cvt_pk_bf16_f32 v69, v74, v75
	global_store_dwordx4 v[78:79], v[66:69], off offset:256
	v_pk_add_f32 v[8:9], v[8:9], 0 op_sel_hi:[1,0]
	v_pk_add_f32 v[6:7], v[6:7], 0 op_sel_hi:[1,0]
	v_pk_add_f32 v[68:69], v[60:61], 0 op_sel_hi:[1,0]
	v_pk_add_f32 v[60:61], v[58:59], 0 op_sel_hi:[1,0]
	v_cvt_pk_bf16_f32 v58, v62, v63
	v_add_co_u32_e32 v62, vcc, s71, v134
	v_cvt_pk_bf16_f32 v59, v64, v65
	v_cvt_pk_bf16_f32 v60, v60, v61
	v_cvt_pk_bf16_f32 v61, v68, v69
	v_lshl_add_u64 v[66:67], v[134:135], 0, s[8:9]
	s_nop 0
	v_addc_co_u32_e32 v63, vcc, 0, v135, vcc
	global_store_dwordx4 v[62:63], v[58:61], off
	s_nop 0
	s_nop 1
	v_pk_add_f32 v[58:59], v[48:49], 0 op_sel_hi:[1,0]
	v_pk_add_f32 v[48:49], v[46:47], 0 op_sel_hi:[1,0]
	v_cvt_pk_bf16_f32 v46, v54, v55
	v_cvt_pk_bf16_f32 v47, v56, v57
	s_nop 0
	v_cvt_pk_bf16_f32 v48, v48, v49
	v_cvt_pk_bf16_f32 v49, v58, v59
	global_store_dwordx4 v[66:67], v[46:49], off offset:256
	s_nop 0
	s_nop 1
	v_pk_add_f32 v[48:49], v[52:53], 0 op_sel_hi:[1,0]
	v_pk_add_f32 v[52:53], v[44:45], 0 op_sel_hi:[1,0]
	v_pk_add_f32 v[44:45], v[42:43], 0 op_sel_hi:[1,0]
	v_cvt_pk_bf16_f32 v42, v50, v51
	v_cvt_pk_bf16_f32 v43, v48, v49
	v_add_co_u32_e32 v48, vcc, s72, v134
	v_cvt_pk_bf16_f32 v44, v44, v45
	v_cvt_pk_bf16_f32 v45, v52, v53
	v_lshl_add_u64 v[46:47], v[134:135], 0, s[10:11]
	s_nop 0
	v_addc_co_u32_e32 v49, vcc, 0, v135, vcc
	global_store_dwordx4 v[48:49], v[42:45], off
	s_nop 0
	s_nop 1
	v_pk_add_f32 v[42:43], v[32:33], 0 op_sel_hi:[1,0]
	v_pk_add_f32 v[32:33], v[30:31], 0 op_sel_hi:[1,0]
	v_cvt_pk_bf16_f32 v30, v38, v39
	v_cvt_pk_bf16_f32 v31, v40, v41
	s_nop 0
	v_cvt_pk_bf16_f32 v32, v32, v33
	v_cvt_pk_bf16_f32 v33, v42, v43
	global_store_dwordx4 v[46:47], v[30:33], off offset:256
	s_nop 0
	s_nop 1
	v_pk_add_f32 v[32:33], v[36:37], 0 op_sel_hi:[1,0]
	v_pk_add_f32 v[36:37], v[28:29], 0 op_sel_hi:[1,0]
	v_pk_add_f32 v[28:29], v[26:27], 0 op_sel_hi:[1,0]
	v_cvt_pk_bf16_f32 v26, v34, v35
	v_cvt_pk_bf16_f32 v27, v32, v33
	v_add_co_u32_e32 v32, vcc, s73, v134
	v_cvt_pk_bf16_f32 v28, v28, v29
	v_cvt_pk_bf16_f32 v29, v36, v37
	v_lshl_add_u64 v[30:31], v[134:135], 0, s[12:13]
	s_nop 0
	v_addc_co_u32_e32 v33, vcc, 0, v135, vcc
	global_store_dwordx4 v[32:33], v[26:29], off
	s_nop 0
	s_nop 1
	v_pk_add_f32 v[26:27], v[16:17], 0 op_sel_hi:[1,0]
	v_pk_add_f32 v[16:17], v[14:15], 0 op_sel_hi:[1,0]
	v_cvt_pk_bf16_f32 v14, v22, v23
	v_cvt_pk_bf16_f32 v15, v24, v25
	s_nop 0
	v_cvt_pk_bf16_f32 v16, v16, v17
	v_cvt_pk_bf16_f32 v17, v26, v27
	global_store_dwordx4 v[30:31], v[14:17], off offset:256
	s_nop 0
	s_nop 1
	v_pk_add_f32 v[16:17], v[20:21], 0 op_sel_hi:[1,0]
	v_pk_add_f32 v[20:21], v[12:13], 0 op_sel_hi:[1,0]
	v_pk_add_f32 v[12:13], v[10:11], 0 op_sel_hi:[1,0]
	v_cvt_pk_bf16_f32 v10, v18, v19
	v_cvt_pk_bf16_f32 v11, v16, v17
	v_add_co_u32_e32 v16, vcc, s74, v134
	v_lshl_add_u64 v[14:15], v[134:135], 0, s[14:15]
	s_nop 0
	v_addc_co_u32_e32 v17, vcc, 0, v135, vcc
	v_cvt_pk_bf16_f32 v12, v12, v13
	v_cvt_pk_bf16_f32 v13, v20, v21
	global_store_dwordx4 v[16:17], v[10:13], off
	s_andn2_b64 vcc, exec, s[16:17]
	s_mov_b64 s[16:17], -1
	v_pk_add_f32 v[10:11], v[4:5], 0 op_sel_hi:[1,0]
	v_pk_add_f32 v[4:5], v[2:3], 0 op_sel_hi:[1,0]
	v_cvt_pk_bf16_f32 v2, v6, v7
	v_cvt_pk_bf16_f32 v3, v8, v9
	s_nop 0
	v_cvt_pk_bf16_f32 v4, v4, v5
	v_cvt_pk_bf16_f32 v5, v10, v11
	global_store_dwordx4 v[14:15], v[2:5], off offset:256
	s_cbranch_vccnz .LBB0_717
	s_andn2_b64 vcc, exec, s[0:1]
	s_cbranch_vccnz .LBB0_716
	s_barrier
	s_branch .LBB0_716

.LBB0_737:
	s_cmpk_gt_i32 s10, 0x15ff
	s_mov_b64 s[2:3], -1
	s_cbranch_scc0 .LBB0_739
	s_and_b32 s3, s14, 0x1ffc0
	s_and_b32 s2, s12, 0x7c0
	v_or_b32_e32 v2, s3, v76
	v_or_b32_e32 v1, s2, v77
	v_lshlrev_b32_e32 v66, 13, v2
	v_lshl_add_u64 v[2:3], s[48:49], 0, v[66:67]
	v_lshlrev_b32_e32 v66, 2, v1
	v_lshl_add_u64 v[62:63], v[2:3], 0, v[66:67]
	v_add_co_u32_e32 v10, vcc, 0x8000, v62
	v_or_b32_e32 v1, s2, v79
	s_nop 0
	v_addc_co_u32_e32 v11, vcc, 0, v63, vcc
	v_add_co_u32_e32 v18, vcc, 0x10000, v62
	global_load_dwordx4 v[2:5], v[62:63], off
	global_load_dwordx4 v[6:9], v[10:11], off
	v_addc_co_u32_e32 v19, vcc, 0, v63, vcc
	v_add_co_u32_e32 v20, vcc, 0x18000, v62
	s_lshl_b32 s4, s3, 1
	s_nop 0
	v_addc_co_u32_e32 v21, vcc, 0, v63, vcc
	v_add_co_u32_e32 v26, vcc, 0x20000, v62
	global_load_dwordx4 v[10:13], v[18:19], off
	global_load_dwordx4 v[14:17], v[20:21], off
	v_addc_co_u32_e32 v27, vcc, 0, v63, vcc
	v_add_co_u32_e32 v28, vcc, 0x28000, v62
	v_mul_u32_u24_e32 v1, 0x1600, v1
	s_nop 0
	v_addc_co_u32_e32 v29, vcc, 0, v63, vcc
	v_add_co_u32_e32 v34, vcc, 0x30000, v62
	global_load_dwordx4 v[18:21], v[26:27], off
	global_load_dwordx4 v[22:25], v[28:29], off
	v_addc_co_u32_e32 v35, vcc, 0, v63, vcc
	v_add_co_u32_e32 v36, vcc, 0x38000, v62
	v_lshlrev_b32_e32 v66, 1, v1
	s_nop 0
	v_addc_co_u32_e32 v37, vcc, 0, v63, vcc
	v_add_co_u32_e32 v42, vcc, 0x40000, v62
	global_load_dwordx4 v[26:29], v[34:35], off
	global_load_dwordx4 v[30:33], v[36:37], off
	v_addc_co_u32_e32 v43, vcc, 0, v63, vcc
	v_add_co_u32_e32 v44, vcc, 0x48000, v62
	v_or_b32_e32 v1, s2, v81
	s_nop 0
	v_addc_co_u32_e32 v45, vcc, 0, v63, vcc
	v_add_co_u32_e32 v50, vcc, 0x50000, v62
	global_load_dwordx4 v[34:37], v[42:43], off
	global_load_dwordx4 v[38:41], v[44:45], off
	v_addc_co_u32_e32 v51, vcc, 0, v63, vcc
	v_add_co_u32_e32 v52, vcc, 0x58000, v62
	v_mul_u32_u24_e32 v1, 0x1600, v1
	s_nop 0
	v_addc_co_u32_e32 v53, vcc, 0, v63, vcc
	v_add_co_u32_e32 v58, vcc, 0x60000, v62
	global_load_dwordx4 v[42:45], v[50:51], off
	global_load_dwordx4 v[46:49], v[52:53], off
	v_addc_co_u32_e32 v59, vcc, 0, v63, vcc
	v_add_co_u32_e32 v60, vcc, 0x68000, v62
	s_nop 1
	v_addc_co_u32_e32 v61, vcc, 0, v63, vcc
	global_load_dwordx4 v[50:53], v[58:59], off
	global_load_dwordx4 v[54:57], v[60:61], off
	v_add_co_u32_e32 v58, vcc, 0x70000, v62
	s_nop 1
	v_addc_co_u32_e32 v59, vcc, 0, v63, vcc
	global_load_dwordx4 v[58:61], v[58:59], off
	v_add_co_u32_e32 v62, vcc, 0x78000, v62
	s_nop 1
	v_addc_co_u32_e32 v63, vcc, 0, v63, vcc
	global_load_dwordx4 v[62:65], v[62:63], off
	s_waitcnt vmcnt(0)
	ds_write2_b32 v78, v2, v3 offset1:1
	ds_write2_b32 v78, v4, v5 offset0:2 offset1:3
	ds_write2_b32 v88, v6, v7 offset1:1
	ds_write2_b32 v89, v8, v9 offset1:1
	ds_write2_b32 v90, v10, v11 offset1:1
	ds_write2_b32 v91, v12, v13 offset1:1
	ds_write2_b32 v92, v14, v15 offset1:1
	ds_write2_b32 v93, v16, v17 offset1:1
	ds_write2_b32 v94, v18, v19 offset1:1
	ds_write2_b32 v95, v20, v21 offset1:1
	ds_write2_b32 v96, v22, v23 offset1:1
	ds_write2_b32 v97, v24, v25 offset1:1
	ds_write2_b32 v98, v26, v27 offset1:1
	ds_write2_b32 v99, v28, v29 offset1:1
	ds_write2_b32 v100, v30, v31 offset1:1
	ds_write2_b32 v101, v32, v33 offset1:1
	ds_write2_b32 v102, v34, v35 offset1:1
	ds_write2_b32 v103, v36, v37 offset1:1
	ds_write2_b32 v104, v38, v39 offset1:1
	ds_write2_b32 v105, v40, v41 offset1:1
	ds_write2_b32 v106, v42, v43 offset1:1
	ds_write2_b32 v107, v44, v45 offset1:1
	ds_write2_b32 v108, v46, v47 offset1:1
	ds_write2_b32 v109, v48, v49 offset1:1
	ds_write2_b32 v110, v50, v51 offset1:1
	ds_write2_b32 v111, v52, v53 offset1:1
	ds_write2_b32 v112, v54, v55 offset1:1
	ds_write2_b32 v113, v56, v57 offset1:1
	ds_write2_b32 v114, v58, v59 offset1:1
	ds_write2_b32 v115, v60, v61 offset1:1
	ds_write2_b32 v116, v62, v63 offset1:1
	ds_write2_b32 v117, v64, v65 offset1:1
	s_waitcnt lgkmcnt(0)
	ds_read2_b32 v[10:11], v118 offset0:134 offset1:142
	ds_read2_b32 v[8:9], v118 offset0:199 offset1:207
	ds_read2_b32 v[14:15], v118 offset0:4 offset1:12
	ds_read2_b32 v[12:13], v118 offset0:69 offset1:77
	ds_read2_b32 v[18:19], v80 offset0:130 offset1:138
	s_waitcnt lgkmcnt(4)
	s_waitcnt lgkmcnt(3)
	ds_read2_b32 v[16:17], v80 offset0:195 offset1:203
	v_cvt_pk_bf16_f32 v7, v10, v8
	s_waitcnt lgkmcnt(3)
	ds_read2_b32 v[22:23], v80 offset1:8
	s_waitcnt lgkmcnt(3)
	ds_read2_b32 v[20:21], v80 offset0:65 offset1:73
	v_cvt_pk_bf16_f32 v6, v14, v12
	s_waitcnt lgkmcnt(3)
	s_waitcnt lgkmcnt(2)
	s_waitcnt lgkmcnt(1)
	v_cvt_pk_bf16_f32 v5, v18, v16
	s_waitcnt lgkmcnt(0)
	v_lshl_add_u64 v[2:3], v[68:69], 0, s[4:5]
	v_cvt_pk_bf16_f32 v4, v22, v20
	v_lshl_add_u64 v[24:25], v[2:3], 0, v[66:67]
	global_store_dwordx4 v[24:25], v[4:7], off
	s_nop 1
	v_cvt_pk_bf16_f32 v7, v11, v9
	v_cvt_pk_bf16_f32 v6, v15, v13
	v_cvt_pk_bf16_f32 v5, v19, v17
	ds_read2_b32 v[12:13], v118 offset0:150 offset1:158
	v_cvt_pk_bf16_f32 v4, v23, v21
	ds_read2_b32 v[8:9], v118 offset0:215 offset1:223
	v_lshlrev_b32_e32 v66, 1, v1
	v_lshl_add_u64 v[10:11], v[2:3], 0, v[66:67]
	ds_read2_b32 v[14:15], v118 offset0:20 offset1:28
	global_store_dwordx4 v[10:11], v[4:7], off
	ds_read2_b32 v[10:11], v118 offset0:85 offset1:93
	ds_read2_b32 v[18:19], v80 offset0:146 offset1:154
	s_waitcnt lgkmcnt(4)
	s_waitcnt lgkmcnt(3)
	ds_read2_b32 v[16:17], v80 offset0:211 offset1:219
	v_cvt_pk_bf16_f32 v7, v12, v8
	s_waitcnt lgkmcnt(3)
	ds_read2_b32 v[22:23], v80 offset0:16 offset1:24
	s_waitcnt lgkmcnt(3)
	ds_read2_b32 v[20:21], v80 offset0:81 offset1:89
	v_cvt_pk_bf16_f32 v6, v14, v10
	s_waitcnt lgkmcnt(3)
	s_waitcnt lgkmcnt(2)
	v_or_b32_e32 v1, s2, v82
	s_waitcnt lgkmcnt(1)
	v_cvt_pk_bf16_f32 v5, v18, v16
	s_waitcnt lgkmcnt(0)
	v_mul_u32_u24_e32 v1, 0x1600, v1
	v_lshlrev_b32_e32 v66, 1, v1
	v_cvt_pk_bf16_f32 v4, v22, v20
	v_lshl_add_u64 v[24:25], v[2:3], 0, v[66:67]
	global_store_dwordx4 v[24:25], v[4:7], off
	s_nop 1
	v_cvt_pk_bf16_f32 v7, v13, v9
	v_cvt_pk_bf16_f32 v6, v15, v11
	v_cvt_pk_bf16_f32 v5, v19, v17
	v_or_b32_e32 v1, s2, v83
	ds_read2_b32 v[12:13], v118 offset0:166 offset1:174
	v_cvt_pk_bf16_f32 v4, v23, v21
	v_mul_u32_u24_e32 v1, 0x1600, v1
	ds_read2_b32 v[8:9], v118 offset0:231 offset1:239
	v_lshlrev_b32_e32 v66, 1, v1
	v_lshl_add_u64 v[10:11], v[2:3], 0, v[66:67]
	ds_read2_b32 v[14:15], v118 offset0:36 offset1:44
	global_store_dwordx4 v[10:11], v[4:7], off
	ds_read2_b32 v[10:11], v118 offset0:101 offset1:109
	ds_read2_b32 v[18:19], v80 offset0:162 offset1:170
	s_waitcnt lgkmcnt(4)
	s_waitcnt lgkmcnt(3)
	ds_read2_b32 v[16:17], v80 offset0:227 offset1:235
	v_cvt_pk_bf16_f32 v7, v12, v8
	s_waitcnt lgkmcnt(3)
	ds_read2_b32 v[22:23], v80 offset0:32 offset1:40
	s_waitcnt lgkmcnt(3)
	ds_read2_b32 v[20:21], v80 offset0:97 offset1:105
	v_cvt_pk_bf16_f32 v6, v14, v10
	s_waitcnt lgkmcnt(3)
	s_waitcnt lgkmcnt(2)
	v_or_b32_e32 v1, s2, v84
	s_waitcnt lgkmcnt(1)
	v_cvt_pk_bf16_f32 v5, v18, v16
	s_waitcnt lgkmcnt(0)
	v_mul_u32_u24_e32 v1, 0x1600, v1
	v_lshlrev_b32_e32 v66, 1, v1
	v_cvt_pk_bf16_f32 v4, v22, v20
	v_lshl_add_u64 v[24:25], v[2:3], 0, v[66:67]
	global_store_dwordx4 v[24:25], v[4:7], off
	s_nop 1
	v_cvt_pk_bf16_f32 v7, v13, v9
	v_cvt_pk_bf16_f32 v6, v15, v11
	v_cvt_pk_bf16_f32 v5, v19, v17
	v_or_b32_e32 v1, s2, v85
	ds_read2_b32 v[12:13], v118 offset0:182 offset1:190
	v_cvt_pk_bf16_f32 v4, v23, v21
	v_mul_u32_u24_e32 v1, 0x1600, v1
	ds_read2_b32 v[8:9], v118 offset0:247 offset1:255
	v_lshlrev_b32_e32 v66, 1, v1
	v_lshl_add_u64 v[10:11], v[2:3], 0, v[66:67]
	ds_read2_b32 v[14:15], v118 offset0:52 offset1:60
	global_store_dwordx4 v[10:11], v[4:7], off
	ds_read2_b32 v[10:11], v118 offset0:117 offset1:125
	ds_read2_b32 v[18:19], v80 offset0:178 offset1:186
	s_waitcnt lgkmcnt(4)
	s_waitcnt lgkmcnt(3)
	ds_read2_b32 v[16:17], v80 offset0:243 offset1:251
	v_cvt_pk_bf16_f32 v7, v12, v8
	s_waitcnt lgkmcnt(3)
	ds_read2_b32 v[22:23], v80 offset0:48 offset1:56
	s_waitcnt lgkmcnt(3)
	ds_read2_b32 v[20:21], v80 offset0:113 offset1:121
	v_cvt_pk_bf16_f32 v6, v14, v10
	s_waitcnt lgkmcnt(3)
	s_waitcnt lgkmcnt(2)
	v_or_b32_e32 v1, s2, v86
	s_waitcnt lgkmcnt(1)
	v_cvt_pk_bf16_f32 v5, v18, v16
	s_waitcnt lgkmcnt(0)
	v_mul_u32_u24_e32 v1, 0x1600, v1
	v_lshlrev_b32_e32 v66, 1, v1
	v_cvt_pk_bf16_f32 v4, v22, v20
	v_lshl_add_u64 v[24:25], v[2:3], 0, v[66:67]
	global_store_dwordx4 v[24:25], v[4:7], off
	v_or_b32_e32 v1, s2, v87
	v_bfe_u32 v8, v23, 16, 1
	v_cvt_pk_bf16_f32 v7, v13, v9
	v_cvt_pk_bf16_f32 v6, v15, v11
	v_cvt_pk_bf16_f32 v5, v19, v17
	v_bfe_u32 v4, v21, 16, 1
	v_add3_u32 v8, v23, v8, s17
	v_mul_u32_u24_e32 v1, 0x1600, v1
	v_add3_u32 v4, v21, v4, s17
	v_lshrrev_b32_e32 v8, 16, v8
	v_lshlrev_b32_e32 v66, 1, v1
	v_and_or_b32 v4, v4, s18, v8
	v_lshl_add_u64 v[2:3], v[2:3], 0, v[66:67]
	global_store_dwordx4 v[2:3], v[4:7], off
	s_waitcnt lgkmcnt(0)
	s_mov_b64 s[2:3], 0

.LBB0_936:
	s_or_b64 exec, exec, s[8:9]
	v_or_b32_e32 v1, 1, v172
	v_min_u32_e32 v1, v1, v170
	v_cvt_f32_ubyte0_e32 v1, v1
	v_div_scale_f32 v30, s[8:9], v1, v1, 1.0
	v_rcp_f32_e32 v31, v30
	v_div_scale_f32 v32, vcc, 1.0, v1, 1.0
	v_mov_b32_e32 v49, v129
	v_fma_f32 v33, -v30, v31, 1.0
	v_fmac_f32_e32 v31, v33, v31
	v_mul_f32_e32 v33, v32, v31
	v_fma_f32 v48, -v30, v33, v32
	v_fmac_f32_e32 v33, v48, v31
	v_fma_f32 v30, -v30, v33, v32
	v_div_fmas_f32 v30, v30, v31, v33
	v_div_fixup_f32 v30, v30, v1, 1.0
	v_mov_b32_e32 v32, v167
	v_mov_b32_e32 v33, v169
	v_mov_b32_e32 v48, v127
	v_pk_fma_f32 v[32:33], v[30:31], v[32:33], v[48:49] op_sel_hi:[0,1,1] neg_lo:[0,0,1] neg_hi:[0,0,1]
	v_mov_b32_e32 v167, v168
	v_mov_b32_e32 v48, v126
	v_mov_b32_e32 v49, v128
	v_pk_fma_f32 v[48:49], v[30:31], v[166:167], v[48:49] op_sel_hi:[0,1,1] neg_lo:[0,0,1] neg_hi:[0,0,1]
	v_mov_b32_e32 v166, v163
	v_mov_b32_e32 v167, v165
	v_mov_b32_e32 v168, v131
	v_mov_b32_e32 v169, v133
	v_mov_b32_e32 v163, v164
	v_mov_b32_e32 v164, v130
	v_mov_b32_e32 v165, v132
	v_pk_fma_f32 v[166:167], v[30:31], v[166:167], v[168:169] op_sel_hi:[0,1,1] neg_lo:[0,0,1] neg_hi:[0,0,1]
	v_pk_fma_f32 v[30:31], v[30:31], v[162:163], v[164:165] op_sel_hi:[0,1,1] neg_lo:[0,0,1] neg_hi:[0,0,1]
	v_bfe_u32 v1, v31, 16, 1
	v_bfe_u32 v162, v30, 16, 1
	v_bfe_u32 v163, v49, 16, 1
	v_bfe_u32 v164, v48, 16, 1
	v_add3_u32 v49, v49, v163, s17
	v_add3_u32 v30, v30, v162, s17
	v_add3_u32 v1, v31, v1, s17
	v_bfe_u32 v31, v32, 16, 1
	v_bfe_u32 v162, v33, 16, 1
	v_bfe_u32 v163, v166, 16, 1
	v_add3_u32 v48, v48, v164, s17
	v_bfe_u32 v164, v167, 16, 1
	v_add3_u32 v163, v166, v163, s17
	v_add3_u32 v33, v33, v162, s17
	v_add3_u32 v31, v32, v31, s17
	v_add3_u32 v164, v167, v164, s17
	v_lshrrev_b32_e32 v162, 16, v31
	v_lshrrev_b32_e32 v31, 16, v33
	v_lshrrev_b32_e32 v32, 16, v163
	v_lshrrev_b32_e32 v33, 16, v164
	v_and_or_b32 v32, v30, s16, v32
	v_and_or_b32 v31, v49, s16, v31
	v_and_or_b32 v30, v48, s16, v162
	v_lshlrev_b64 v[48:49], 12, v[94:95]
	v_and_or_b32 v33, v1, s16, v33
	v_lshl_add_u64 v[48:49], v[92:93], 0, v[48:49]
	global_store_dwordx4 v[48:49], v[30:33], off
	s_nop 0
	s_nop 1
	v_and_b32_e32 v30, 0xffff0000, v26
	v_lshlrev_b32_e32 v31, 16, v26
	v_pk_add_f32 v[32:33], v[30:31], 0 op_sel_hi:[1,0]
	v_and_b32_e32 v26, 0xffff0000, v27
	v_lshlrev_b32_e32 v27, 16, v27
	v_pk_add_f32 v[164:165], v[32:33], v[126:127]
	v_pk_add_f32 v[32:33], v[26:27], 0 op_sel_hi:[1,0]
	s_nop 0
	v_pk_add_f32 v[166:167], v[32:33], v[128:129]
	v_and_b32_e32 v32, 0xffff0000, v28
	v_lshlrev_b32_e32 v33, 16, v28
	v_and_b32_e32 v28, 0xffff0000, v29
	v_lshlrev_b32_e32 v29, 16, v29
	v_pk_add_f32 v[48:49], v[32:33], 0 op_sel_hi:[1,0]
	v_pk_add_f32 v[162:163], v[28:29], 0 op_sel_hi:[1,0]
	v_pk_add_f32 v[48:49], v[48:49], v[130:131]
	v_pk_add_f32 v[162:163], v[162:163], v[132:133]
	s_and_saveexec_b64 s[8:9], s[2:3]
	s_cbranch_execnz .LBB0_1040
	s_or_b64 exec, exec, s[8:9]
	s_and_saveexec_b64 s[8:9], s[2:3]
	s_cbranch_execnz .LBB0_1041

.LBB0_1326:
	s_andn2_b64 vcc, exec, s[40:41]
	s_cbranch_vccnz .LBB0_1328
	s_cmpk_eq_i32 s38, 0x400
	v_mov_b32_e32 v1, v194
	v_mov_b32_e32 v3, v195
	s_cselect_b32 s40, 0, 0x1000
	s_add_u32 s40, s6, s40
	v_lshl_add_u32 v4, v3, 3, s64
	v_ashrrev_i32_e32 v5, 31, v4
	s_addc_u32 s41, s7, 0
	v_add_u32_e32 v3, s65, v1
	v_lshl_add_u64 v[4:5], v[4:5], 1, s[40:41]
	v_mad_i64_i32 v[134:135], s[40:41], v3, s57, v[4:5]
	v_add_co_u32_e32 v136, vcc, s56, v134
	global_load_dwordx4 v[200:203], v[134:135], off
	s_nop 0
	v_addc_co_u32_e32 v137, vcc, 0, v135, vcc
	global_load_dwordx4 v[204:207], v[136:137], off
	global_load_dwordx4 v[208:211], v[136:137], off offset:256
	global_load_dwordx4 v[212:215], v[134:135], off offset:256
	v_add_u32_e32 v1, 16, v3
	v_add_u32_e32 v134, 32, v3
	v_add_u32_e32 v135, 48, v3
	v_mad_i64_i32 v[138:139], s[40:41], v1, s57, v[4:5]
	v_mad_i64_i32 v[140:141], s[40:41], v134, s57, v[4:5]
	v_mad_i64_i32 v[146:147], s[40:41], v135, s57, v[4:5]
	global_load_dwordx4 v[216:219], v[138:139], off
	global_load_dwordx4 v[166:169], v[138:139], off offset:256
	global_load_dwordx4 v[158:161], v[140:141], off
	global_load_dwordx4 v[150:153], v[140:141], off offset:256
	global_load_dwordx4 v[142:145], v[146:147], off
	global_load_dwordx4 v[134:137], v[146:147], off offset:256
	v_add_co_u32_e32 v138, vcc, s56, v138
	s_nop 1
	v_addc_co_u32_e32 v139, vcc, 0, v139, vcc
	global_load_dwordx4 v[220:223], v[138:139], off
	global_load_dwordx4 v[170:173], v[138:139], off offset:256
	v_add_co_u32_e32 v140, vcc, s56, v140
	s_nop 1
	v_addc_co_u32_e32 v141, vcc, 0, v141, vcc
	global_load_dwordx4 v[162:165], v[140:141], off
	global_load_dwordx4 v[154:157], v[140:141], off offset:256
	v_add_co_u32_e32 v138, vcc, s56, v146
	s_nop 1
	v_addc_co_u32_e32 v139, vcc, 0, v147, vcc
	global_load_dwordx4 v[146:149], v[138:139], off
	s_nop 0
	global_load_dwordx4 v[138:141], v[138:139], off offset:256
	s_waitcnt vmcnt(6)
	v_lshlrev_b32_e32 v226, 16, v202
	v_and_b32_e32 v228, 0xffff0000, v204
	v_and_b32_e32 v230, 0xffff0000, v205
	v_lshlrev_b32_e32 v231, 16, v206
	v_lshlrev_b32_e32 v233, 16, v207
	v_and_b32_e32 v234, 0xffff0000, v207
	v_lshlrev_b32_e32 v229, 16, v205
	v_rcp_f32_e32 v205, v228
	v_rcp_f32_e32 v207, v230
	v_rcp_f32_e32 v228, v231
	v_rcp_f32_e32 v230, v233
	v_rcp_f32_e32 v231, v234
	v_and_b32_e32 v227, 0xffff0000, v202
	v_lshlrev_b32_e32 v202, 16, v203
	v_and_b32_e32 v203, 0xffff0000, v203
	v_lshlrev_b32_e32 v1, 16, v204
	v_rcp_f32_e32 v204, v1
	v_pk_mul_f32 v[202:203], v[230:231], v[202:203]
	v_lshlrev_b32_e32 v1, 16, v209
	v_pk_mul_f32 v[128:129], v[128:129], v[202:203]
	v_rcp_f32_e32 v202, v1
	v_and_b32_e32 v1, 0xffff0000, v209
	v_rcp_f32_e32 v203, v1
	v_lshlrev_b32_e32 v224, 16, v200
	v_and_b32_e32 v225, 0xffff0000, v200
	v_and_b32_e32 v232, 0xffff0000, v206
	v_rcp_f32_e32 v206, v229
	v_lshlrev_b32_e32 v235, 16, v208
	v_and_b32_e32 v208, 0xffff0000, v208
	v_pk_mul_f32 v[204:205], v[204:205], v[224:225]
	v_rcp_f32_e32 v229, v232
	v_rcp_f32_e32 v232, v235
	v_rcp_f32_e32 v233, v208
	v_pk_mul_f32 v[130:131], v[130:131], v[204:205]
	v_lshlrev_b32_e32 v204, 16, v213
	v_and_b32_e32 v205, 0xffff0000, v213
	v_lshlrev_b32_e32 v1, 16, v210
	v_lshlrev_b32_e32 v200, 16, v201
	v_and_b32_e32 v201, 0xffff0000, v201
	v_pk_mul_f32 v[202:203], v[202:203], v[204:205]
	v_rcp_f32_e32 v204, v1
	v_and_b32_e32 v1, 0xffff0000, v210
	v_pk_mul_f32 v[200:201], v[206:207], v[200:201]
	v_rcp_f32_e32 v205, v1
	v_lshlrev_b32_e32 v1, 16, v211
	v_pk_mul_f32 v[132:133], v[132:133], v[200:201]
	v_lshlrev_b32_e32 v200, 16, v212
	v_and_b32_e32 v201, 0xffff0000, v212
	v_rcp_f32_e32 v208, v1
	v_and_b32_e32 v1, 0xffff0000, v211
	v_pk_mul_f32 v[206:207], v[228:229], v[226:227]
	v_pk_mul_f32 v[200:201], v[232:233], v[200:201]
	v_rcp_f32_e32 v209, v1
	v_pk_mul_f32 v[126:127], v[126:127], v[206:207]
	v_lshlrev_b32_e32 v206, 16, v214
	v_and_b32_e32 v207, 0xffff0000, v214
	v_pk_mul_f32 v[122:123], v[122:123], v[200:201]
	v_pk_mul_f32 v[204:205], v[204:205], v[206:207]
	v_pk_mul_f32 v[124:125], v[124:125], v[202:203]
	v_pk_mul_f32 v[118:119], v[118:119], v[204:205]
	v_lshlrev_b32_e32 v202, 16, v216
	v_and_b32_e32 v203, 0xffff0000, v216
	v_lshlrev_b32_e32 v206, 16, v215
	v_and_b32_e32 v207, 0xffff0000, v215
	v_pk_mul_f32 v[206:207], v[208:209], v[206:207]
	s_waitcnt vmcnt(0)
	v_lshlrev_b32_e32 v1, 16, v220
	v_rcp_f32_e32 v200, v1
	v_and_b32_e32 v1, 0xffff0000, v220
	v_rcp_f32_e32 v201, v1
	v_lshlrev_b32_e32 v1, 16, v221
	v_rcp_f32_e32 v204, v1
	v_and_b32_e32 v1, 0xffff0000, v221
	v_rcp_f32_e32 v205, v1
	v_pk_mul_f32 v[200:201], v[200:201], v[202:203]
	v_lshlrev_b32_e32 v202, 16, v217
	v_and_b32_e32 v203, 0xffff0000, v217
	v_lshlrev_b32_e32 v1, 16, v222
	v_pk_mul_f32 v[202:203], v[204:205], v[202:203]
	v_rcp_f32_e32 v204, v1
	v_and_b32_e32 v1, 0xffff0000, v222
	v_rcp_f32_e32 v205, v1
	v_lshlrev_b32_e32 v1, 16, v223
	v_rcp_f32_e32 v208, v1
	v_and_b32_e32 v1, 0xffff0000, v223
	v_rcp_f32_e32 v209, v1
	v_lshlrev_b32_e32 v1, 16, v170
	v_pk_mul_f32 v[114:115], v[114:115], v[200:201]
	v_rcp_f32_e32 v200, v1
	v_and_b32_e32 v1, 0xffff0000, v170
	v_rcp_f32_e32 v201, v1
	v_lshlrev_b32_e32 v1, 16, v171
	v_rcp_f32_e32 v170, v1
	v_and_b32_e32 v1, 0xffff0000, v171
	v_rcp_f32_e32 v171, v1
	v_pk_mul_f32 v[116:117], v[116:117], v[202:203]
	v_lshlrev_b32_e32 v202, 16, v166
	v_and_b32_e32 v203, 0xffff0000, v166
	v_lshlrev_b32_e32 v166, 16, v167
	v_and_b32_e32 v167, 0xffff0000, v167
	v_lshlrev_b32_e32 v1, 16, v172
	v_pk_mul_f32 v[166:167], v[170:171], v[166:167]
	v_rcp_f32_e32 v170, v1
	v_and_b32_e32 v1, 0xffff0000, v172
	v_rcp_f32_e32 v171, v1
	v_lshlrev_b32_e32 v1, 16, v173
	v_rcp_f32_e32 v172, v1
	v_and_b32_e32 v1, 0xffff0000, v173
	v_rcp_f32_e32 v173, v1
	v_lshlrev_b32_e32 v1, 16, v162
	v_pk_mul_f32 v[108:109], v[108:109], v[166:167]
	v_rcp_f32_e32 v166, v1
	v_and_b32_e32 v1, 0xffff0000, v162
	v_rcp_f32_e32 v167, v1
	v_lshlrev_b32_e32 v1, 16, v163
	v_rcp_f32_e32 v162, v1
	v_and_b32_e32 v1, 0xffff0000, v163
	v_rcp_f32_e32 v163, v1
	v_pk_mul_f32 v[200:201], v[200:201], v[202:203]
	v_lshlrev_b32_e32 v202, 16, v168
	v_and_b32_e32 v203, 0xffff0000, v168
	v_lshlrev_b32_e32 v168, 16, v169
	v_and_b32_e32 v169, 0xffff0000, v169
	v_pk_mul_f32 v[168:169], v[172:173], v[168:169]
	v_lshlrev_b32_e32 v1, 16, v164
	v_pk_mul_f32 v[104:105], v[104:105], v[168:169]
	v_lshlrev_b32_e32 v168, 16, v158
	v_and_b32_e32 v169, 0xffff0000, v158
	v_lshlrev_b32_e32 v158, 16, v159
	v_and_b32_e32 v159, 0xffff0000, v159
	v_pk_mul_f32 v[158:159], v[162:163], v[158:159]
	v_rcp_f32_e32 v162, v1
	v_and_b32_e32 v1, 0xffff0000, v164
	v_rcp_f32_e32 v163, v1
	v_lshlrev_b32_e32 v1, 16, v165
	v_rcp_f32_e32 v164, v1
	v_and_b32_e32 v1, 0xffff0000, v165
	v_rcp_f32_e32 v165, v1
	v_lshlrev_b32_e32 v1, 16, v154
	v_pk_mul_f32 v[100:101], v[100:101], v[158:159]
	v_rcp_f32_e32 v158, v1
	v_and_b32_e32 v1, 0xffff0000, v154
	v_rcp_f32_e32 v159, v1
	v_lshlrev_b32_e32 v1, 16, v155
	v_rcp_f32_e32 v154, v1
	v_and_b32_e32 v1, 0xffff0000, v155
	v_rcp_f32_e32 v155, v1
	v_pk_mul_f32 v[166:167], v[166:167], v[168:169]
	v_lshlrev_b32_e32 v168, 16, v160
	v_and_b32_e32 v169, 0xffff0000, v160
	v_lshlrev_b32_e32 v160, 16, v161
	v_and_b32_e32 v161, 0xffff0000, v161
	v_pk_mul_f32 v[160:161], v[164:165], v[160:161]
	v_lshlrev_b32_e32 v1, 16, v156
	v_pk_mul_f32 v[96:97], v[96:97], v[160:161]
	v_lshlrev_b32_e32 v160, 16, v150
	v_and_b32_e32 v161, 0xffff0000, v150
	v_lshlrev_b32_e32 v150, 16, v151
	v_and_b32_e32 v151, 0xffff0000, v151
	v_pk_mul_f32 v[150:151], v[154:155], v[150:151]
	v_rcp_f32_e32 v154, v1
	v_and_b32_e32 v1, 0xffff0000, v156
	v_rcp_f32_e32 v155, v1
	v_lshlrev_b32_e32 v1, 16, v157
	v_rcp_f32_e32 v156, v1
	v_and_b32_e32 v1, 0xffff0000, v157
	v_rcp_f32_e32 v157, v1
	v_lshlrev_b32_e32 v1, 16, v146
	v_pk_mul_f32 v[92:93], v[92:93], v[150:151]
	v_rcp_f32_e32 v150, v1
	v_and_b32_e32 v1, 0xffff0000, v146
	v_rcp_f32_e32 v151, v1
	v_pk_mul_f32 v[158:159], v[158:159], v[160:161]
	v_lshlrev_b32_e32 v160, 16, v152
	v_and_b32_e32 v161, 0xffff0000, v152
	v_lshlrev_b32_e32 v152, 16, v153
	v_and_b32_e32 v153, 0xffff0000, v153
	v_pk_mul_f32 v[152:153], v[156:157], v[152:153]
	v_pk_mul_f32 v[154:155], v[154:155], v[160:161]
	v_pk_mul_f32 v[88:89], v[88:89], v[152:153]
	v_lshlrev_b32_e32 v152, 16, v142
	v_and_b32_e32 v153, 0xffff0000, v142
	v_pk_mul_f32 v[150:151], v[150:151], v[152:153]
	v_lshlrev_b32_e32 v152, 16, v144
	v_and_b32_e32 v153, 0xffff0000, v144
	v_add_u32_e32 v144, 0x80, v3
	v_pk_mul_f32 v[86:87], v[86:87], v[154:155]
	v_mad_i64_i32 v[154:155], s[40:41], v144, s57, v[4:5]
	v_add_co_u32_e32 v156, vcc, s56, v154
	v_lshlrev_b32_e32 v1, 16, v147
	s_nop 0
	v_addc_co_u32_e32 v157, vcc, 0, v155, vcc
	v_pk_mul_f32 v[170:171], v[170:171], v[202:203]
	v_pk_mul_f32 v[106:107], v[106:107], v[200:201]
	v_rcp_f32_e32 v146, v1
	v_and_b32_e32 v1, 0xffff0000, v147
	global_load_dwordx4 v[200:203], v[156:157], off
	v_rcp_f32_e32 v147, v1
	v_pk_mul_f32 v[120:121], v[120:121], v[206:207]
	v_lshlrev_b32_e32 v206, 16, v218
	v_and_b32_e32 v207, 0xffff0000, v218
	v_lshlrev_b32_e32 v142, 16, v143
	v_and_b32_e32 v143, 0xffff0000, v143
	v_lshlrev_b32_e32 v1, 16, v148
	v_pk_mul_f32 v[204:205], v[204:205], v[206:207]
	v_lshlrev_b32_e32 v206, 16, v219
	v_and_b32_e32 v207, 0xffff0000, v219
	v_pk_mul_f32 v[142:143], v[146:147], v[142:143]
	v_rcp_f32_e32 v146, v1
	v_and_b32_e32 v1, 0xffff0000, v148
	v_pk_mul_f32 v[206:207], v[208:209], v[206:207]
	v_rcp_f32_e32 v147, v1
	v_lshlrev_b32_e32 v1, 16, v149
	v_pk_mul_f32 v[112:113], v[112:113], v[206:207]
	v_pk_mul_f32 v[110:111], v[110:111], v[204:205]
	v_rcp_f32_e32 v148, v1
	v_and_b32_e32 v1, 0xffff0000, v149
	global_load_dwordx4 v[204:207], v[154:155], off
	global_load_dwordx4 v[212:215], v[154:155], off offset:256
	v_rcp_f32_e32 v149, v1
	v_lshlrev_b32_e32 v1, 16, v138
	v_pk_mul_f32 v[84:85], v[84:85], v[142:143]
	v_rcp_f32_e32 v142, v1
	v_and_b32_e32 v1, 0xffff0000, v138
	v_rcp_f32_e32 v143, v1
	v_lshlrev_b32_e32 v1, 16, v139
	v_rcp_f32_e32 v138, v1
	v_and_b32_e32 v1, 0xffff0000, v139
	v_rcp_f32_e32 v139, v1
	v_lshlrev_b32_e32 v144, 16, v145
	v_and_b32_e32 v145, 0xffff0000, v145
	global_load_dwordx4 v[208:211], v[156:157], off offset:256
	v_pk_mul_f32 v[144:145], v[148:149], v[144:145]
	v_lshlrev_b32_e32 v1, 16, v140
	v_pk_mul_f32 v[80:81], v[80:81], v[144:145]
	v_lshlrev_b32_e32 v144, 16, v134
	v_and_b32_e32 v145, 0xffff0000, v134
	v_lshlrev_b32_e32 v134, 16, v135
	v_and_b32_e32 v135, 0xffff0000, v135
	v_pk_mul_f32 v[134:135], v[138:139], v[134:135]
	v_rcp_f32_e32 v138, v1
	v_and_b32_e32 v1, 0xffff0000, v140
	v_rcp_f32_e32 v139, v1
	v_lshlrev_b32_e32 v1, 16, v141
	v_rcp_f32_e32 v140, v1
	v_and_b32_e32 v1, 0xffff0000, v141
	v_rcp_f32_e32 v141, v1
	v_pk_mul_f32 v[142:143], v[142:143], v[144:145]
	v_lshlrev_b32_e32 v144, 16, v136
	v_and_b32_e32 v145, 0xffff0000, v136
	v_lshlrev_b32_e32 v136, 16, v137
	v_and_b32_e32 v137, 0xffff0000, v137
	v_add_u32_e32 v1, 0x90, v3
	v_pk_mul_f32 v[136:137], v[140:141], v[136:137]
	v_pk_mul_f32 v[76:77], v[76:77], v[134:135]
	v_mad_i64_i32 v[134:135], s[40:41], v1, s57, v[4:5]
	v_pk_mul_f32 v[72:73], v[72:73], v[136:137]
	v_add_co_u32_e32 v136, vcc, s56, v134
	v_pk_mul_f32 v[102:103], v[102:103], v[170:171]
	v_pk_mul_f32 v[162:163], v[162:163], v[168:169]
	v_pk_mul_f32 v[98:99], v[98:99], v[166:167]
	v_addc_co_u32_e32 v137, vcc, 0, v135, vcc
	global_load_dwordx4 v[216:219], v[134:135], off
	global_load_dwordx4 v[166:169], v[134:135], off offset:256
	global_load_dwordx4 v[220:223], v[136:137], off
	global_load_dwordx4 v[170:173], v[136:137], off offset:256
	v_add_u32_e32 v1, 0xa0, v3
	v_mad_i64_i32 v[134:135], s[40:41], v1, s57, v[4:5]
	v_add_co_u32_e32 v136, vcc, s56, v134
	v_pk_mul_f32 v[94:95], v[94:95], v[162:163]
	v_pk_mul_f32 v[90:91], v[90:91], v[158:159]
	v_pk_mul_f32 v[146:147], v[146:147], v[152:153]
	v_pk_mul_f32 v[82:83], v[82:83], v[150:151]
	v_addc_co_u32_e32 v137, vcc, 0, v135, vcc
	global_load_dwordx4 v[158:161], v[134:135], off
	global_load_dwordx4 v[150:153], v[134:135], off offset:256
	global_load_dwordx4 v[162:165], v[136:137], off
	global_load_dwordx4 v[154:157], v[136:137], off offset:256
	v_add_u32_e32 v1, 0xb0, v3
	v_pk_mul_f32 v[138:139], v[138:139], v[144:145]
	v_mad_i64_i32 v[4:5], s[40:41], v1, s57, v[4:5]
	v_pk_mul_f32 v[70:71], v[70:71], v[138:139]
	v_add_co_u32_e32 v138, vcc, s56, v4
	v_pk_mul_f32 v[78:79], v[78:79], v[146:147]
	s_nop 0
	v_addc_co_u32_e32 v139, vcc, 0, v5, vcc
	v_pk_mul_f32 v[74:75], v[74:75], v[142:143]
	global_load_dwordx4 v[142:145], v[4:5], off
	global_load_dwordx4 v[134:137], v[4:5], off offset:256
	global_load_dwordx4 v[146:149], v[138:139], off
	s_nop 0
	global_load_dwordx4 v[138:141], v[138:139], off offset:256
	s_waitcnt vmcnt(0)
	v_lshlrev_b32_e32 v1, 16, v200
	v_rcp_f32_e32 v4, v1
	v_and_b32_e32 v1, 0xffff0000, v200
	v_rcp_f32_e32 v5, v1
	v_lshlrev_b32_e32 v1, 16, v201
	v_rcp_f32_e32 v200, v1
	v_and_b32_e32 v1, 0xffff0000, v201
	v_rcp_f32_e32 v201, v1
	v_lshlrev_b32_e32 v224, 16, v204
	v_and_b32_e32 v225, 0xffff0000, v204
	v_lshlrev_b32_e32 v204, 16, v205
	v_and_b32_e32 v205, 0xffff0000, v205
	v_lshlrev_b32_e32 v1, 16, v202
	v_pk_mul_f32 v[200:201], v[200:201], v[204:205]
	v_rcp_f32_e32 v204, v1
	v_and_b32_e32 v1, 0xffff0000, v202
	v_rcp_f32_e32 v205, v1
	v_lshlrev_b32_e32 v1, 16, v203
	v_rcp_f32_e32 v202, v1
	v_and_b32_e32 v1, 0xffff0000, v203
	v_rcp_f32_e32 v203, v1
	v_pk_mul_f32 v[4:5], v[4:5], v[224:225]
	v_lshlrev_b32_e32 v1, 16, v208
	v_lshlrev_b32_e32 v224, 16, v206
	v_and_b32_e32 v225, 0xffff0000, v206
	v_lshlrev_b32_e32 v206, 16, v207
	v_and_b32_e32 v207, 0xffff0000, v207
	v_pk_mul_f32 v[66:67], v[66:67], v[4:5]
	v_rcp_f32_e32 v4, v1
	v_and_b32_e32 v1, 0xffff0000, v208
	v_pk_mul_f32 v[202:203], v[202:203], v[206:207]
	v_rcp_f32_e32 v5, v1
	v_lshlrev_b32_e32 v1, 16, v209
	v_pk_mul_f32 v[64:65], v[64:65], v[202:203]
	v_rcp_f32_e32 v202, v1
	v_and_b32_e32 v1, 0xffff0000, v209
	v_rcp_f32_e32 v203, v1
	v_pk_mul_f32 v[68:69], v[68:69], v[200:201]
	v_lshlrev_b32_e32 v200, 16, v212
	v_and_b32_e32 v201, 0xffff0000, v212
	v_pk_mul_f32 v[4:5], v[4:5], v[200:201]
	v_lshlrev_b32_e32 v200, 16, v213
	v_and_b32_e32 v201, 0xffff0000, v213
	v_lshlrev_b32_e32 v1, 16, v210
	v_pk_mul_f32 v[200:201], v[202:203], v[200:201]
	v_rcp_f32_e32 v202, v1
	v_and_b32_e32 v1, 0xffff0000, v210
	v_rcp_f32_e32 v203, v1
	v_lshlrev_b32_e32 v1, 16, v211
	v_rcp_f32_e32 v206, v1
	v_and_b32_e32 v1, 0xffff0000, v211
	v_pk_mul_f32 v[204:205], v[204:205], v[224:225]
	v_rcp_f32_e32 v207, v1
	v_pk_mul_f32 v[62:63], v[62:63], v[204:205]
	v_lshlrev_b32_e32 v1, 16, v220
	v_lshlrev_b32_e32 v204, 16, v214
	v_and_b32_e32 v205, 0xffff0000, v214
	v_pk_mul_f32 v[58:59], v[58:59], v[4:5]
	v_rcp_f32_e32 v4, v1
	v_and_b32_e32 v1, 0xffff0000, v220
	v_pk_mul_f32 v[202:203], v[202:203], v[204:205]
	v_rcp_f32_e32 v5, v1
	v_lshlrev_b32_e32 v1, 16, v221
	v_pk_mul_f32 v[54:55], v[54:55], v[202:203]
	v_rcp_f32_e32 v202, v1
	v_and_b32_e32 v1, 0xffff0000, v221
	v_rcp_f32_e32 v203, v1
	v_pk_mul_f32 v[60:61], v[60:61], v[200:201]
	v_lshlrev_b32_e32 v200, 16, v216
	v_and_b32_e32 v201, 0xffff0000, v216
	v_pk_mul_f32 v[4:5], v[4:5], v[200:201]
	v_lshlrev_b32_e32 v200, 16, v217
	v_and_b32_e32 v201, 0xffff0000, v217
	v_lshlrev_b32_e32 v1, 16, v222
	v_pk_mul_f32 v[200:201], v[202:203], v[200:201]
	v_rcp_f32_e32 v202, v1
	v_and_b32_e32 v1, 0xffff0000, v222
	v_lshlrev_b32_e32 v204, 16, v215
	v_and_b32_e32 v205, 0xffff0000, v215
	v_rcp_f32_e32 v203, v1
	v_lshlrev_b32_e32 v1, 16, v223
	v_pk_mul_f32 v[204:205], v[206:207], v[204:205]
	v_rcp_f32_e32 v206, v1
	v_and_b32_e32 v1, 0xffff0000, v223
	v_rcp_f32_e32 v207, v1
	v_lshlrev_b32_e32 v1, 16, v170
	v_pk_mul_f32 v[50:51], v[50:51], v[4:5]
	v_rcp_f32_e32 v4, v1
	v_and_b32_e32 v1, 0xffff0000, v170
	v_rcp_f32_e32 v5, v1
	v_lshlrev_b32_e32 v1, 16, v171
	v_rcp_f32_e32 v170, v1
	v_and_b32_e32 v1, 0xffff0000, v171
	v_rcp_f32_e32 v171, v1
	v_pk_mul_f32 v[52:53], v[52:53], v[200:201]
	v_lshlrev_b32_e32 v200, 16, v166
	v_and_b32_e32 v201, 0xffff0000, v166
	v_lshlrev_b32_e32 v166, 16, v167
	v_and_b32_e32 v167, 0xffff0000, v167
	v_lshlrev_b32_e32 v1, 16, v172
	v_pk_mul_f32 v[166:167], v[170:171], v[166:167]
	v_rcp_f32_e32 v170, v1
	v_and_b32_e32 v1, 0xffff0000, v172
	v_rcp_f32_e32 v171, v1
	v_lshlrev_b32_e32 v1, 16, v173
	v_rcp_f32_e32 v172, v1
	v_and_b32_e32 v1, 0xffff0000, v173
	v_pk_mul_f32 v[4:5], v[4:5], v[200:201]
	v_rcp_f32_e32 v173, v1
	v_lshlrev_b32_e32 v1, 16, v162
	v_pk_mul_f32 v[42:43], v[42:43], v[4:5]
	v_rcp_f32_e32 v4, v1
	v_and_b32_e32 v1, 0xffff0000, v162
	v_rcp_f32_e32 v5, v1
	v_lshlrev_b32_e32 v1, 16, v163
	v_rcp_f32_e32 v162, v1
	v_and_b32_e32 v1, 0xffff0000, v163
	v_rcp_f32_e32 v163, v1
	v_pk_mul_f32 v[44:45], v[44:45], v[166:167]
	v_lshlrev_b32_e32 v166, 16, v158
	v_and_b32_e32 v167, 0xffff0000, v158
	v_lshlrev_b32_e32 v158, 16, v159
	v_and_b32_e32 v159, 0xffff0000, v159
	v_lshlrev_b32_e32 v1, 16, v164
	v_pk_mul_f32 v[158:159], v[162:163], v[158:159]
	v_rcp_f32_e32 v162, v1
	v_and_b32_e32 v1, 0xffff0000, v164
	v_rcp_f32_e32 v163, v1
	v_lshlrev_b32_e32 v1, 16, v165
	v_rcp_f32_e32 v164, v1
	v_and_b32_e32 v1, 0xffff0000, v165
	v_pk_mul_f32 v[4:5], v[4:5], v[166:167]
	v_rcp_f32_e32 v165, v1
	v_lshlrev_b32_e32 v1, 16, v154
	v_pk_mul_f32 v[34:35], v[34:35], v[4:5]
	v_rcp_f32_e32 v4, v1
	v_and_b32_e32 v1, 0xffff0000, v154
	v_rcp_f32_e32 v5, v1
	v_lshlrev_b32_e32 v1, 16, v155
	v_rcp_f32_e32 v154, v1
	v_and_b32_e32 v1, 0xffff0000, v155
	v_rcp_f32_e32 v155, v1
	v_pk_mul_f32 v[36:37], v[36:37], v[158:159]
	v_lshlrev_b32_e32 v158, 16, v150
	v_and_b32_e32 v159, 0xffff0000, v150
	v_lshlrev_b32_e32 v150, 16, v151
	v_and_b32_e32 v151, 0xffff0000, v151
	v_lshlrev_b32_e32 v1, 16, v156
	v_pk_mul_f32 v[150:151], v[154:155], v[150:151]
	v_rcp_f32_e32 v154, v1
	v_and_b32_e32 v1, 0xffff0000, v156
	v_rcp_f32_e32 v155, v1
	v_lshlrev_b32_e32 v1, 16, v157
	v_rcp_f32_e32 v156, v1
	v_and_b32_e32 v1, 0xffff0000, v157
	v_pk_mul_f32 v[4:5], v[4:5], v[158:159]
	v_rcp_f32_e32 v157, v1
	v_lshlrev_b32_e32 v1, 16, v146
	v_pk_mul_f32 v[26:27], v[26:27], v[4:5]
	v_rcp_f32_e32 v4, v1
	v_and_b32_e32 v1, 0xffff0000, v146
	v_rcp_f32_e32 v5, v1
	v_lshlrev_b32_e32 v1, 16, v147
	v_rcp_f32_e32 v146, v1
	v_and_b32_e32 v1, 0xffff0000, v147
	v_rcp_f32_e32 v147, v1
	v_pk_mul_f32 v[28:29], v[28:29], v[150:151]
	v_lshlrev_b32_e32 v150, 16, v142
	v_and_b32_e32 v151, 0xffff0000, v142
	v_lshlrev_b32_e32 v142, 16, v143
	v_and_b32_e32 v143, 0xffff0000, v143
	v_lshlrev_b32_e32 v1, 16, v148
	v_pk_mul_f32 v[142:143], v[146:147], v[142:143]
	v_rcp_f32_e32 v146, v1
	v_and_b32_e32 v1, 0xffff0000, v148
	v_rcp_f32_e32 v147, v1
	v_lshlrev_b32_e32 v1, 16, v149
	v_rcp_f32_e32 v148, v1
	v_and_b32_e32 v1, 0xffff0000, v149
	v_pk_mul_f32 v[4:5], v[4:5], v[150:151]
	v_rcp_f32_e32 v149, v1
	v_lshlrev_b32_e32 v1, 16, v138
	v_pk_mul_f32 v[18:19], v[18:19], v[4:5]
	v_rcp_f32_e32 v4, v1
	v_and_b32_e32 v1, 0xffff0000, v138
	v_rcp_f32_e32 v5, v1
	v_lshlrev_b32_e32 v1, 16, v139
	v_rcp_f32_e32 v138, v1
	v_and_b32_e32 v1, 0xffff0000, v139
	v_rcp_f32_e32 v139, v1
	v_pk_mul_f32 v[20:21], v[20:21], v[142:143]
	v_lshlrev_b32_e32 v142, 16, v134
	v_and_b32_e32 v143, 0xffff0000, v134
	v_lshlrev_b32_e32 v134, 16, v135
	v_and_b32_e32 v135, 0xffff0000, v135
	v_lshlrev_b32_e32 v1, 16, v140
	v_pk_mul_f32 v[134:135], v[138:139], v[134:135]
	v_rcp_f32_e32 v138, v1
	v_and_b32_e32 v1, 0xffff0000, v140
	v_rcp_f32_e32 v139, v1
	v_lshlrev_b32_e32 v1, 16, v141
	v_rcp_f32_e32 v140, v1
	v_and_b32_e32 v1, 0xffff0000, v141
	v_rcp_f32_e32 v141, v1
	v_pk_mul_f32 v[56:57], v[56:57], v[204:205]
	v_lshlrev_b32_e32 v204, 16, v218
	v_and_b32_e32 v205, 0xffff0000, v218
	v_pk_mul_f32 v[202:203], v[202:203], v[204:205]
	v_lshlrev_b32_e32 v204, 16, v219
	v_and_b32_e32 v205, 0xffff0000, v219
	v_lshlrev_b32_e32 v200, 16, v168
	v_and_b32_e32 v201, 0xffff0000, v168
	v_lshlrev_b32_e32 v168, 16, v169
	v_and_b32_e32 v169, 0xffff0000, v169
	v_lshlrev_b32_e32 v166, 16, v160
	v_and_b32_e32 v167, 0xffff0000, v160
	v_lshlrev_b32_e32 v160, 16, v161
	v_and_b32_e32 v161, 0xffff0000, v161
	v_lshlrev_b32_e32 v158, 16, v152
	v_and_b32_e32 v159, 0xffff0000, v152
	v_lshlrev_b32_e32 v152, 16, v153
	v_and_b32_e32 v153, 0xffff0000, v153
	v_lshlrev_b32_e32 v150, 16, v144
	v_and_b32_e32 v151, 0xffff0000, v144
	v_lshlrev_b32_e32 v144, 16, v145
	v_and_b32_e32 v145, 0xffff0000, v145
	v_pk_mul_f32 v[4:5], v[4:5], v[142:143]
	v_lshlrev_b32_e32 v142, 16, v136
	v_and_b32_e32 v143, 0xffff0000, v136
	v_lshlrev_b32_e32 v136, 16, v137
	v_and_b32_e32 v137, 0xffff0000, v137
	s_waitcnt vmcnt(0)
	v_pk_mul_f32 v[204:205], v[206:207], v[204:205]
	v_pk_mul_f32 v[170:171], v[170:171], v[200:201]
	v_pk_mul_f32 v[168:169], v[172:173], v[168:169]
	v_pk_mul_f32 v[162:163], v[162:163], v[166:167]
	v_pk_mul_f32 v[160:161], v[164:165], v[160:161]
	v_pk_mul_f32 v[154:155], v[154:155], v[158:159]
	v_pk_mul_f32 v[152:153], v[156:157], v[152:153]
	v_pk_mul_f32 v[146:147], v[146:147], v[150:151]
	v_pk_mul_f32 v[144:145], v[148:149], v[144:145]
	v_pk_mul_f32 v[138:139], v[138:139], v[142:143]
	v_pk_mul_f32 v[136:137], v[140:141], v[136:137]
	v_pk_mul_f32 v[48:49], v[48:49], v[204:205]
	v_pk_mul_f32 v[46:47], v[46:47], v[202:203]
	v_pk_mul_f32 v[40:41], v[40:41], v[168:169]
	v_pk_mul_f32 v[38:39], v[38:39], v[170:171]
	v_pk_mul_f32 v[32:33], v[32:33], v[160:161]
	v_pk_mul_f32 v[30:31], v[30:31], v[162:163]
	v_pk_mul_f32 v[24:25], v[24:25], v[152:153]
	v_pk_mul_f32 v[22:23], v[22:23], v[154:155]
	v_pk_mul_f32 v[16:17], v[16:17], v[144:145]
	v_pk_mul_f32 v[14:15], v[14:15], v[146:147]
	v_pk_mul_f32 v[12:13], v[12:13], v[134:135]
	v_pk_mul_f32 v[10:11], v[10:11], v[4:5]
	v_pk_mul_f32 v[8:9], v[8:9], v[136:137]
	v_pk_mul_f32 v[6:7], v[6:7], v[138:139]
